# v44 + nt on prologue bf16 weight stores and conv output stores (write-once streams)
# baseline (speedup 1.0000x reference)
; __device__ __forceinline__ unsigned cvtpk(float lo, float hi) { return pg8::cvt_pk_bf16(lo, hi); }
; __device__ __forceinline__ float bflo(unsigned w) { return __uint_as_float(w << 16); }
; __device__ __forceinline__ float bfhi(unsigned w) { return __uint_as_float(w & 0xffff0000u); }
; __device__ __forceinline__ float gelu_tanh(float x) { const float y = x * (1.0f + 0.044715f * x * x); return x * rcp(1.0f + ex2(-2.0f * 0.7978845608028654f * LOG2E * y)); }
; __device__ __forceinline__ void convgelu_phase(const bf16* __restrict__ Z, const float* __restrict__ cw, const float* __restrict__ cb, bf16* __restrict__ H, int G, const int tid_in) {
;     ...
;         for (int n4 = 0; n4 < CG_ROWS; n4 += 4) {
;             v4u gq[4], uq[4];
; #pragma unroll
;             for (int i = 0; i < 4; ++i) { gq[i] = *(const v4u*)(zp + (size_t)(n4 + i) * FF2); uq[i] = *(const v4u*)(zp + (size_t)(n4 + i) * FF2 + FF); }
; #pragma unroll
;             for (int i = 0; i < 4; ++i) { const v4u g0 = gq[i], u0 = uq[i];
;                 float o[8];
; #pragma unroll
;                 for (int e = 0; e < 4; ++e) {
;                     const float ga = bg[2 * e] + wg[0][2 * e] * bflo(g2[e]) + wg[1][2 * e] * bflo(g1[e]) + wg[2][2 * e] * bflo(g0[e]);
;                     const float gb = bg[2 * e + 1] + wg[0][2 * e + 1] * bfhi(g2[e]) + wg[1][2 * e + 1] * bfhi(g1[e]) + wg[2][2 * e + 1] * bfhi(g0[e]);
;                     const float ua = bu[2 * e] + wu[0][2 * e] * bflo(u2[e]) + wu[1][2 * e] * bflo(u1[e]) + wu[2][2 * e] * bflo(u0[e]);
;                     const float ub = bu[2 * e + 1] + wu[0][2 * e + 1] * bfhi(u2[e]) + wu[1][2 * e + 1] * bfhi(u1[e]) + wu[2][2 * e + 1] * bfhi(u0[e]);
;                     o[2 * e] = gelu_tanh(ga) * ua; o[2 * e + 1] = gelu_tanh(gb) * ub;
;                 }
;                 v4u w; w.x = cvtpk(o[0], o[1]); w.y = cvtpk(o[2], o[3]); w.z = cvtpk(o[4], o[5]); w.w = cvtpk(o[6], o[7]);
;                 *(v4u*)(hp + (size_t)(n4 + i) * FF) = w;
.LBB0_102:
	v_lshl_add_u64 v[64:65], v[118:119], 0, v[114:115]
	v_add_co_u32_e32 v66, vcc, 0x2cc00000, v64
	s_waitcnt vmcnt(3)
	v_lshlrev_b32_e32 v120, 16, v86
	v_addc_co_u32_e32 v67, vcc, 0, v65, vcc
	global_load_dwordx4 v[110:113], v[66:67], off nt
	v_add_co_u32_e32 v66, vcc, 0x2cc02000, v64
	v_and_b32_e32 v121, 0xffff0000, v86
	s_nop 0
	v_addc_co_u32_e32 v67, vcc, 0, v65, vcc
	global_load_dwordx4 v[106:109], v[66:67], off offset:3072 nt
	s_waitcnt vmcnt(4)
	v_pk_fma_f32 v[120:121], v[4:5], v[120:121], v[52:53]
	v_lshlrev_b32_e32 v124, 16, v80
	v_and_b32_e32 v125, 0xffff0000, v80
	v_pk_fma_f32 v[122:123], v[20:21], v[124:125], v[120:121]
	v_add_co_u32_e32 v66, vcc, 0x2cc05000, v64
	s_waitcnt vmcnt(2)
	v_lshlrev_b32_e32 v126, 16, v94
	v_addc_co_u32_e32 v67, vcc, 0, v65, vcc
	v_and_b32_e32 v127, 0xffff0000, v94
	global_load_dwordx4 v[102:105], v[66:67], off offset:2048 nt
	v_lshlrev_b32_e32 v86, 16, v87
	v_and_b32_e32 v87, 0xffff0000, v87
	v_pk_fma_f32 v[86:87], v[6:7], v[86:87], v[54:55]
	v_add_co_u32_e32 v66, vcc, 0x2cc08000, v64
	v_lshlrev_b32_e32 v134, 16, v82
	s_nop 0
	v_addc_co_u32_e32 v67, vcc, 0, v65, vcc
	global_load_dwordx4 v[98:101], v[66:67], off offset:1024 nt
	v_and_b32_e32 v135, 0xffff0000, v82
	v_lshlrev_b32_e32 v144, 16, v83
	v_and_b32_e32 v145, 0xffff0000, v83
	v_lshlrev_b32_e32 v136, 16, v96
	v_and_b32_e32 v137, 0xffff0000, v96
	v_add_co_u32_e32 v66, vcc, 0x2cc0b000, v64
	v_lshlrev_b32_e32 v146, 16, v97
	s_nop 0
	v_addc_co_u32_e32 v67, vcc, 0, v65, vcc
	v_and_b32_e32 v147, 0xffff0000, v97
	global_load_dwordx4 v[72:75], v[66:67], off nt
	v_add_co_u32_e32 v66, vcc, 0x2cc0d000, v64
	s_mov_b32 s4, 0x37c00000
	s_nop 0
	v_addc_co_u32_e32 v67, vcc, 0, v65, vcc
	global_load_dwordx4 v[68:71], v[66:67], off offset:3072 nt
	v_add_co_u32_e32 v66, vcc, 0x2cc10000, v64
	s_add_i32 s28, s28, 4
	s_nop 0
	v_addc_co_u32_e32 v67, vcc, 0, v65, vcc
	v_add_co_u32_e32 v64, vcc, 0x2cc13000, v64
	global_load_dwordx4 v[76:79], v[66:67], off offset:2048 nt
	s_nop 0
	v_addc_co_u32_e32 v65, vcc, 0, v65, vcc
	global_load_dwordx4 v[64:67], v[64:65], off offset:1024 nt
	s_cmp_gt_u32 s28, 11
	s_waitcnt vmcnt(7)
	v_lshlrev_b32_e32 v120, 16, v110
	v_and_b32_e32 v121, 0xffff0000, v110
	v_pk_fma_f32 v[128:129], v[36:37], v[120:121], v[122:123]
	v_lshlrev_b32_e32 v122, 16, v90
	v_mul_f32_e32 v80, 0x3d372713, v128
	v_fma_f32 v80, v128, v80, 1.0
	v_mul_f32_e32 v80, v128, v80
	v_mul_f32_e32 v80, 0xc0135761, v80
	v_exp_f32_e32 v80, v80
	v_and_b32_e32 v123, 0xffff0000, v90
	v_pk_fma_f32 v[122:123], v[12:13], v[122:123], v[60:61]
	v_lshlrev_b32_e32 v110, 16, v95
	v_add_f32_e32 v80, 1.0, v80
	v_rcp_f32_e32 v132, v80
	v_mul_f32_e32 v80, 0x3d372713, v129
	v_fma_f32 v80, v129, v80, 1.0
	v_mul_f32_e32 v80, v129, v80
	v_mul_f32_e32 v80, 0xc0135761, v80
	v_exp_f32_e32 v80, v80
	v_pk_fma_f32 v[130:131], v[28:29], v[126:127], v[122:123]
	s_waitcnt vmcnt(6)
	v_lshlrev_b32_e32 v122, 16, v106
	v_and_b32_e32 v123, 0xffff0000, v106
	v_add_f32_e32 v80, 1.0, v80
	v_rcp_f32_e32 v133, v80
	v_pk_fma_f32 v[130:131], v[44:45], v[122:123], v[130:131]
	v_lshlrev_b32_e32 v80, 16, v111
	v_pk_mul_f32 v[128:129], v[128:129], v[132:133]
	s_nop 0
	v_pk_mul_f32 v[130:131], v[130:131], v[128:129]
	v_lshlrev_b32_e32 v128, 16, v81
	v_and_b32_e32 v129, 0xffff0000, v81
	v_pk_fma_f32 v[86:87], v[22:23], v[128:129], v[86:87]
	v_and_b32_e32 v81, 0xffff0000, v111
	v_pk_fma_f32 v[132:133], v[38:39], v[80:81], v[86:87]
	v_and_b32_e32 v111, 0xffff0000, v95
	v_mul_f32_e32 v84, 0x3d372713, v132
	v_fma_f32 v84, v132, v84, 1.0
	v_mul_f32_e32 v84, v132, v84
	v_mul_f32_e32 v84, 0xc0135761, v84
	v_exp_f32_e32 v84, v84
	v_lshlrev_b32_e32 v86, 16, v91
	v_and_b32_e32 v87, 0xffff0000, v91
	v_pk_fma_f32 v[86:87], v[14:15], v[86:87], v[62:63]
	v_add_f32_e32 v84, 1.0, v84
	v_rcp_f32_e32 v94, v84
	v_mul_f32_e32 v84, 0x3d372713, v133
	v_fma_f32 v84, v133, v84, 1.0
	v_mul_f32_e32 v84, v133, v84
	v_mul_f32_e32 v84, 0xc0135761, v84
	v_exp_f32_e32 v84, v84
	v_pk_fma_f32 v[90:91], v[30:31], v[110:111], v[86:87]
	v_lshlrev_b32_e32 v86, 16, v107
	v_and_b32_e32 v87, 0xffff0000, v107
	v_add_f32_e32 v84, 1.0, v84
	v_rcp_f32_e32 v95, v84
	v_pk_fma_f32 v[90:91], v[46:47], v[86:87], v[90:91]
	v_pk_mul_f32 v[94:95], v[132:133], v[94:95]
	s_nop 0
	v_pk_mul_f32 v[106:107], v[90:91], v[94:95]
	v_lshlrev_b32_e32 v90, 16, v88
	v_and_b32_e32 v91, 0xffff0000, v88
	v_pk_fma_f32 v[90:91], v[0:1], v[90:91], v[48:49]
	v_lshlrev_b32_e32 v88, 16, v89
	v_pk_fma_f32 v[94:95], v[16:17], v[134:135], v[90:91]
	v_lshlrev_b32_e32 v90, 16, v112
	v_and_b32_e32 v91, 0xffff0000, v112
	v_pk_fma_f32 v[132:133], v[32:33], v[90:91], v[94:95]
	v_and_b32_e32 v89, 0xffff0000, v89
	v_mul_f32_e32 v82, 0x3d372713, v132
	v_fma_f32 v82, v132, v82, 1.0
	v_mul_f32_e32 v82, v132, v82
	v_mul_f32_e32 v82, 0xc0135761, v82
	v_exp_f32_e32 v82, v82
	v_pk_fma_f32 v[88:89], v[2:3], v[88:89], v[50:51]
	v_lshlrev_b32_e32 v94, 16, v92
	v_and_b32_e32 v95, 0xffff0000, v92
	v_add_f32_e32 v82, 1.0, v82
	v_rcp_f32_e32 v142, v82
	v_mul_f32_e32 v82, 0x3d372713, v133
	v_fma_f32 v82, v133, v82, 1.0
	v_mul_f32_e32 v82, v133, v82
	v_mul_f32_e32 v82, 0xc0135761, v82
	v_exp_f32_e32 v82, v82
	v_pk_fma_f32 v[94:95], v[8:9], v[94:95], v[56:57]
	v_lshlrev_b32_e32 v92, 16, v93
	v_pk_fma_f32 v[140:141], v[24:25], v[136:137], v[94:95]
	v_add_f32_e32 v82, 1.0, v82
	v_rcp_f32_e32 v143, v82
	v_pk_fma_f32 v[82:83], v[18:19], v[144:145], v[88:89]
	v_lshlrev_b32_e32 v88, 16, v113
	v_and_b32_e32 v89, 0xffff0000, v113
	v_pk_fma_f32 v[82:83], v[34:35], v[88:89], v[82:83]
	v_lshlrev_b32_e32 v94, 16, v108
	v_mul_f32_e32 v84, 0x3d372713, v82
	v_fma_f32 v84, v82, v84, 1.0
	v_mul_f32_e32 v84, v82, v84
	v_mul_f32_e32 v84, 0xc0135761, v84
	v_exp_f32_e32 v84, v84
	v_and_b32_e32 v95, 0xffff0000, v108
	v_and_b32_e32 v93, 0xffff0000, v93
	v_pk_fma_f32 v[140:141], v[40:41], v[94:95], v[140:141]
	v_add_f32_e32 v84, 1.0, v84
	v_rcp_f32_e32 v96, v84
	v_mul_f32_e32 v84, 0x3d372713, v83
	v_fma_f32 v84, v83, v84, 1.0
	v_mul_f32_e32 v84, v83, v84
	v_mul_f32_e32 v84, 0xc0135761, v84
	v_exp_f32_e32 v84, v84
	v_pk_mul_f32 v[132:133], v[132:133], v[142:143]
	v_pk_fma_f32 v[92:93], v[10:11], v[92:93], v[58:59]
	v_pk_mul_f32 v[142:143], v[140:141], v[132:133]
	v_add_f32_e32 v84, 1.0, v84
	v_rcp_f32_e32 v97, v84
	v_pk_fma_f32 v[92:93], v[26:27], v[146:147], v[92:93]
	v_lshlrev_b32_e32 v132, 16, v109
	v_and_b32_e32 v133, 0xffff0000, v109
	v_pk_fma_f32 v[92:93], v[42:43], v[132:133], v[92:93]
	v_pk_mul_f32 v[82:83], v[82:83], v[96:97]
	v_cvt_pk_bf16_f32 v142, v142, v143
	v_pk_mul_f32 v[82:83], v[92:93], v[82:83]
	v_cvt_pk_bf16_f32 v140, v130, v131
	v_cvt_pk_bf16_f32 v143, v82, v83
	v_lshl_add_u64 v[82:83], v[116:117], 0, v[114:115]
	v_add_co_u32_e32 v92, vcc, s4, v82
	v_cvt_pk_bf16_f32 v141, v106, v107
	s_nop 0
	v_addc_co_u32_e32 v93, vcc, 0, v83, vcc
	global_store_dwordx4 v[92:93], v[140:143], off nt
	v_pk_fma_f32 v[92:93], v[4:5], v[124:125], v[52:53]
	s_waitcnt vmcnt(6)
; __device__ __forceinline__ unsigned cvtpk(float lo, float hi) { return pg8::cvt_pk_bf16(lo, hi); }
; __device__ __forceinline__ float bflo(unsigned w) { return __uint_as_float(w << 16); }
; __device__ __forceinline__ float bfhi(unsigned w) { return __uint_as_float(w & 0xffff0000u); }
; __device__ __forceinline__ float gelu_tanh(float x) { const float y = x * (1.0f + 0.044715f * x * x); return x * rcp(1.0f + ex2(-2.0f * 0.7978845608028654f * LOG2E * y)); }
; __device__ __forceinline__ void convgelu_phase(const bf16* __restrict__ Z, const float* __restrict__ cw, const float* __restrict__ cb, bf16* __restrict__ H, int G, const int tid_in) {
;     ...
;             for (int i = 0; i < 4; ++i) { const v4u g0 = gq[i], u0 = uq[i];
;                 float o[8];
; #pragma unroll
;                 for (int e = 0; e < 4; ++e) {
;                     const float ga = bg[2 * e] + wg[0][2 * e] * bflo(g2[e]) + wg[1][2 * e] * bflo(g1[e]) + wg[2][2 * e] * bflo(g0[e]);
;                     const float gb = bg[2 * e + 1] + wg[0][2 * e + 1] * bfhi(g2[e]) + wg[1][2 * e + 1] * bfhi(g1[e]) + wg[2][2 * e + 1] * bfhi(g0[e]);
;                     const float ua = bu[2 * e] + wu[0][2 * e] * bflo(u2[e]) + wu[1][2 * e] * bflo(u1[e]) + wu[2][2 * e] * bflo(u0[e]);
;                     const float ub = bu[2 * e + 1] + wu[0][2 * e + 1] * bfhi(u2[e]) + wu[1][2 * e + 1] * bfhi(u1[e]) + wu[2][2 * e + 1] * bfhi(u0[e]);
;                     o[2 * e] = gelu_tanh(ga) * ua; o[2 * e + 1] = gelu_tanh(gb) * ub;
;                 }
;                 v4u w; w.x = cvtpk(o[0], o[1]); w.y = cvtpk(o[2], o[3]); w.z = cvtpk(o[4], o[5]); w.w = cvtpk(o[6], o[7]);
;                 *(v4u*)(hp + (size_t)(n4 + i) * FF) = w;
	v_lshlrev_b32_e32 v124, 16, v102
	v_pk_fma_f32 v[92:93], v[20:21], v[120:121], v[92:93]
	v_and_b32_e32 v125, 0xffff0000, v102
	v_pk_fma_f32 v[92:93], v[36:37], v[124:125], v[92:93]
	v_pk_fma_f32 v[96:97], v[12:13], v[126:127], v[60:61]
	v_mul_f32_e32 v84, 0x3d372713, v92
	v_fma_f32 v84, v92, v84, 1.0
	v_mul_f32_e32 v84, v92, v84
	v_mul_f32_e32 v84, 0xc0135761, v84
	v_exp_f32_e32 v84, v84
	v_pk_fma_f32 v[96:97], v[28:29], v[122:123], v[96:97]
	s_waitcnt vmcnt(5)
	v_lshlrev_b32_e32 v112, 16, v98
	v_and_b32_e32 v113, 0xffff0000, v98
	v_add_f32_e32 v84, 1.0, v84
	v_rcp_f32_e32 v106, v84
	v_mul_f32_e32 v84, 0x3d372713, v93
	v_fma_f32 v84, v93, v84, 1.0
	v_mul_f32_e32 v84, v93, v84
	v_mul_f32_e32 v84, 0xc0135761, v84
	v_exp_f32_e32 v84, v84
	v_pk_fma_f32 v[96:97], v[44:45], v[112:113], v[96:97]
	v_lshlrev_b32_e32 v108, 16, v103
	v_and_b32_e32 v109, 0xffff0000, v103
	v_add_f32_e32 v84, 1.0, v84
	v_rcp_f32_e32 v107, v84
	v_lshlrev_b32_e32 v102, 16, v104
	v_and_b32_e32 v103, 0xffff0000, v104
	s_mov_b32 s4, 0x37c02000
	v_pk_mul_f32 v[92:93], v[92:93], v[106:107]
	v_lshlrev_b32_e32 v106, 16, v99
	v_pk_mul_f32 v[126:127], v[96:97], v[92:93]
	v_pk_fma_f32 v[92:93], v[6:7], v[128:129], v[54:55]
	v_and_b32_e32 v107, 0xffff0000, v99
	v_pk_fma_f32 v[92:93], v[22:23], v[80:81], v[92:93]
	v_pk_fma_f32 v[96:97], v[14:15], v[110:111], v[62:63]
	v_pk_fma_f32 v[92:93], v[38:39], v[108:109], v[92:93]
	v_pk_fma_f32 v[96:97], v[30:31], v[86:87], v[96:97]
	v_mul_f32_e32 v84, 0x3d372713, v92
	v_fma_f32 v84, v92, v84, 1.0
	v_mul_f32_e32 v84, v92, v84
	v_mul_f32_e32 v84, 0xc0135761, v84
	v_exp_f32_e32 v84, v84
	v_pk_fma_f32 v[96:97], v[46:47], v[106:107], v[96:97]
	v_cvt_pk_bf16_f32 v126, v126, v127
	v_pk_fma_f32 v[80:81], v[6:7], v[80:81], v[54:55]
	v_add_f32_e32 v84, 1.0, v84
	v_rcp_f32_e32 v98, v84
	v_mul_f32_e32 v84, 0x3d372713, v93
	v_fma_f32 v84, v93, v84, 1.0
	v_mul_f32_e32 v84, v93, v84
	v_mul_f32_e32 v84, 0xc0135761, v84
	v_exp_f32_e32 v84, v84
	v_pk_fma_f32 v[80:81], v[22:23], v[108:109], v[80:81]
	v_pk_fma_f32 v[86:87], v[14:15], v[86:87], v[62:63]
	v_add_f32_e32 v84, 1.0, v84
	v_rcp_f32_e32 v99, v84
	v_pk_fma_f32 v[86:87], v[30:31], v[106:107], v[86:87]
	v_pk_mul_f32 v[92:93], v[92:93], v[98:99]
	s_nop 0
	v_pk_mul_f32 v[110:111], v[96:97], v[92:93]
	v_pk_fma_f32 v[92:93], v[0:1], v[134:135], v[48:49]
	v_pk_fma_f32 v[96:97], v[8:9], v[136:137], v[56:57]
	v_pk_fma_f32 v[92:93], v[16:17], v[90:91], v[92:93]
	v_pk_fma_f32 v[96:97], v[24:25], v[94:95], v[96:97]
	v_pk_fma_f32 v[92:93], v[32:33], v[102:103], v[92:93]
	v_lshlrev_b32_e32 v98, 16, v100
	v_mul_f32_e32 v84, 0x3d372713, v92
	v_fma_f32 v84, v92, v84, 1.0
	v_mul_f32_e32 v84, v92, v84
	v_mul_f32_e32 v84, 0xc0135761, v84
	v_exp_f32_e32 v84, v84
	v_and_b32_e32 v99, 0xffff0000, v100
	v_pk_fma_f32 v[96:97], v[40:41], v[98:99], v[96:97]
	v_cvt_pk_bf16_f32 v127, v110, v111
	v_add_f32_e32 v84, 1.0, v84
	v_rcp_f32_e32 v128, v84
	v_mul_f32_e32 v84, 0x3d372713, v93
	v_fma_f32 v84, v93, v84, 1.0
	v_mul_f32_e32 v84, v93, v84
	v_mul_f32_e32 v84, 0xc0135761, v84
	v_exp_f32_e32 v84, v84
	v_pk_fma_f32 v[110:111], v[12:13], v[122:123], v[60:61]
	v_pk_fma_f32 v[94:95], v[8:9], v[94:95], v[56:57]
	v_pk_fma_f32 v[110:111], v[28:29], v[112:113], v[110:111]
	v_add_f32_e32 v84, 1.0, v84
	v_rcp_f32_e32 v129, v84
	v_pk_fma_f32 v[94:95], v[24:25], v[98:99], v[94:95]
	v_pk_mul_f32 v[92:93], v[92:93], v[128:129]
	s_nop 0
	v_pk_mul_f32 v[128:129], v[96:97], v[92:93]
	v_pk_fma_f32 v[92:93], v[2:3], v[144:145], v[50:51]
	v_lshlrev_b32_e32 v96, 16, v105
	v_pk_fma_f32 v[92:93], v[18:19], v[88:89], v[92:93]
	v_and_b32_e32 v97, 0xffff0000, v105
	v_pk_fma_f32 v[104:105], v[34:35], v[96:97], v[92:93]
	v_pk_fma_f32 v[92:93], v[10:11], v[146:147], v[58:59]
	v_mul_f32_e32 v84, 0x3d372713, v104
	v_fma_f32 v84, v104, v84, 1.0
	v_mul_f32_e32 v84, v104, v84
	v_mul_f32_e32 v84, 0xc0135761, v84
	v_exp_f32_e32 v84, v84
	v_pk_fma_f32 v[130:131], v[26:27], v[132:133], v[92:93]
	v_lshlrev_b32_e32 v92, 16, v101
	v_and_b32_e32 v93, 0xffff0000, v101
	v_add_f32_e32 v84, 1.0, v84
	v_pk_fma_f32 v[100:101], v[42:43], v[92:93], v[130:131]
	v_rcp_f32_e32 v130, v84
	v_mul_f32_e32 v84, 0x3d372713, v105
	v_fma_f32 v84, v105, v84, 1.0
	v_mul_f32_e32 v84, v105, v84
	v_mul_f32_e32 v84, 0xc0135761, v84
	v_exp_f32_e32 v84, v84
	v_cvt_pk_bf16_f32 v128, v128, v129
	v_add_f32_e32 v84, 1.0, v84
	v_rcp_f32_e32 v131, v84
	s_nop 0
	v_pk_mul_f32 v[104:105], v[104:105], v[130:131]
	s_nop 0
	v_pk_mul_f32 v[100:101], v[100:101], v[104:105]
	s_waitcnt vmcnt(4)
	v_lshlrev_b32_e32 v104, 16, v72
	v_cvt_pk_bf16_f32 v129, v100, v101
	v_add_co_u32_e32 v100, vcc, s4, v82
	v_and_b32_e32 v105, 0xffff0000, v72
	s_nop 0
	v_addc_co_u32_e32 v101, vcc, 0, v83, vcc
	global_store_dwordx4 v[100:101], v[126:129], off offset:3072 nt
	v_pk_fma_f32 v[100:101], v[4:5], v[120:121], v[52:53]
	s_waitcnt vmcnt(4)
; __device__ __forceinline__ unsigned cvtpk(float lo, float hi) { return pg8::cvt_pk_bf16(lo, hi); }
; __device__ __forceinline__ float bflo(unsigned w) { return __uint_as_float(w << 16); }
; __device__ __forceinline__ float bfhi(unsigned w) { return __uint_as_float(w & 0xffff0000u); }
; __device__ __forceinline__ float gelu_tanh(float x) { const float y = x * (1.0f + 0.044715f * x * x); return x * rcp(1.0f + ex2(-2.0f * 0.7978845608028654f * LOG2E * y)); }
; __device__ __forceinline__ void convgelu_phase(const bf16* __restrict__ Z, const float* __restrict__ cw, const float* __restrict__ cb, bf16* __restrict__ H, int G, const int tid_in) {
;     ...
;             for (int i = 0; i < 4; ++i) { const v4u g0 = gq[i], u0 = uq[i];
;                 float o[8];
; #pragma unroll
;                 for (int e = 0; e < 4; ++e) {
;                     const float ga = bg[2 * e] + wg[0][2 * e] * bflo(g2[e]) + wg[1][2 * e] * bflo(g1[e]) + wg[2][2 * e] * bflo(g0[e]);
;                     const float gb = bg[2 * e + 1] + wg[0][2 * e + 1] * bfhi(g2[e]) + wg[1][2 * e + 1] * bfhi(g1[e]) + wg[2][2 * e + 1] * bfhi(g0[e]);
;                     const float ua = bu[2 * e] + wu[0][2 * e] * bflo(u2[e]) + wu[1][2 * e] * bflo(u1[e]) + wu[2][2 * e] * bflo(u0[e]);
;                     const float ub = bu[2 * e + 1] + wu[0][2 * e + 1] * bfhi(u2[e]) + wu[1][2 * e + 1] * bfhi(u1[e]) + wu[2][2 * e + 1] * bfhi(u0[e]);
;                     o[2 * e] = gelu_tanh(ga) * ua; o[2 * e + 1] = gelu_tanh(gb) * ub;
;                 }
;                 v4u w; w.x = cvtpk(o[0], o[1]); w.y = cvtpk(o[2], o[3]); w.z = cvtpk(o[4], o[5]); w.w = cvtpk(o[6], o[7]);
;                 *(v4u*)(hp + (size_t)(n4 + i) * FF) = w;
	v_lshlrev_b32_e32 v120, 16, v68
	v_pk_fma_f32 v[100:101], v[20:21], v[124:125], v[100:101]
	v_and_b32_e32 v121, 0xffff0000, v68
	v_pk_fma_f32 v[100:101], v[36:37], v[104:105], v[100:101]
	v_pk_fma_f32 v[110:111], v[44:45], v[120:121], v[110:111]
	v_mul_f32_e32 v84, 0x3d372713, v100
	v_fma_f32 v84, v100, v84, 1.0
	v_mul_f32_e32 v84, v100, v84
	v_mul_f32_e32 v84, 0xc0135761, v84
	v_exp_f32_e32 v84, v84
	v_lshlrev_b32_e32 v130, 16, v71
	v_and_b32_e32 v131, 0xffff0000, v71
	s_mov_b32 s4, 0x37c05000
	v_add_f32_e32 v84, 1.0, v84
	v_rcp_f32_e32 v122, v84
	v_mul_f32_e32 v84, 0x3d372713, v101
	v_fma_f32 v84, v101, v84, 1.0
	v_mul_f32_e32 v84, v101, v84
	v_mul_f32_e32 v84, 0xc0135761, v84
	v_exp_f32_e32 v84, v84
	s_nop 0
	v_add_f32_e32 v84, 1.0, v84
	v_rcp_f32_e32 v123, v84
	s_nop 0
	v_pk_mul_f32 v[100:101], v[100:101], v[122:123]
	s_nop 0
	v_pk_mul_f32 v[100:101], v[110:111], v[100:101]
	v_lshlrev_b32_e32 v110, 16, v73
	v_and_b32_e32 v111, 0xffff0000, v73
	v_pk_fma_f32 v[80:81], v[38:39], v[110:111], v[80:81]
	v_lshlrev_b32_e32 v122, 16, v69
	v_mul_f32_e32 v84, 0x3d372713, v80
	v_fma_f32 v84, v80, v84, 1.0
	v_mul_f32_e32 v84, v80, v84
	v_mul_f32_e32 v84, 0xc0135761, v84
	v_exp_f32_e32 v84, v84
	v_and_b32_e32 v123, 0xffff0000, v69
	v_pk_fma_f32 v[86:87], v[46:47], v[122:123], v[86:87]
	v_add_f32_e32 v84, 1.0, v84
	v_rcp_f32_e32 v126, v84
	v_mul_f32_e32 v84, 0x3d372713, v81
	v_fma_f32 v84, v81, v84, 1.0
	v_mul_f32_e32 v84, v81, v84
	v_mul_f32_e32 v84, 0xc0135761, v84
	v_exp_f32_e32 v84, v84
	s_nop 0
	v_add_f32_e32 v84, 1.0, v84
	v_rcp_f32_e32 v127, v84
	s_nop 0
	v_pk_mul_f32 v[80:81], v[80:81], v[126:127]
	s_nop 0
	v_pk_mul_f32 v[80:81], v[86:87], v[80:81]
	v_pk_fma_f32 v[86:87], v[0:1], v[90:91], v[48:49]
	v_lshlrev_b32_e32 v90, 16, v74
	v_pk_fma_f32 v[86:87], v[16:17], v[102:103], v[86:87]
	v_and_b32_e32 v91, 0xffff0000, v74
	v_pk_fma_f32 v[86:87], v[32:33], v[90:91], v[86:87]
	v_lshlrev_b32_e32 v126, 16, v70
	v_mul_f32_e32 v84, 0x3d372713, v86
	v_fma_f32 v84, v86, v84, 1.0
	v_mul_f32_e32 v84, v86, v84
	v_mul_f32_e32 v84, 0xc0135761, v84
	v_exp_f32_e32 v84, v84
	v_and_b32_e32 v127, 0xffff0000, v70
	v_pk_fma_f32 v[94:95], v[40:41], v[126:127], v[94:95]
	v_add_f32_e32 v84, 1.0, v84
	v_rcp_f32_e32 v128, v84
	v_mul_f32_e32 v84, 0x3d372713, v87
	v_fma_f32 v84, v87, v84, 1.0
	v_mul_f32_e32 v84, v87, v84
	v_mul_f32_e32 v84, 0xc0135761, v84
	v_exp_f32_e32 v84, v84
	s_nop 0
	v_add_f32_e32 v84, 1.0, v84
	v_rcp_f32_e32 v129, v84
	s_nop 0
	v_pk_mul_f32 v[86:87], v[86:87], v[128:129]
	s_nop 0
	v_pk_mul_f32 v[94:95], v[94:95], v[86:87]
	v_pk_fma_f32 v[86:87], v[2:3], v[88:89], v[50:51]
	v_lshlrev_b32_e32 v128, 16, v75
	v_pk_fma_f32 v[86:87], v[18:19], v[96:97], v[86:87]
	v_and_b32_e32 v129, 0xffff0000, v75
	v_pk_fma_f32 v[86:87], v[34:35], v[128:129], v[86:87]
	v_pk_fma_f32 v[88:89], v[10:11], v[132:133], v[58:59]
	v_mul_f32_e32 v84, 0x3d372713, v86
	v_fma_f32 v84, v86, v84, 1.0
	v_mul_f32_e32 v84, v86, v84
	v_mul_f32_e32 v84, 0xc0135761, v84
	v_exp_f32_e32 v84, v84
	v_pk_fma_f32 v[88:89], v[26:27], v[92:93], v[88:89]
	v_pk_fma_f32 v[92:93], v[10:11], v[92:93], v[58:59]
	v_pk_fma_f32 v[88:89], v[42:43], v[130:131], v[88:89]
	v_add_f32_e32 v84, 1.0, v84
	v_rcp_f32_e32 v132, v84
	v_mul_f32_e32 v84, 0x3d372713, v87
	v_fma_f32 v84, v87, v84, 1.0
	v_mul_f32_e32 v84, v87, v84
	v_mul_f32_e32 v84, 0xc0135761, v84
	v_exp_f32_e32 v84, v84
	v_pk_fma_f32 v[92:93], v[26:27], v[130:131], v[92:93]
	v_add_f32_e32 v84, 1.0, v84
	v_rcp_f32_e32 v133, v84
	s_nop 0
	v_pk_mul_f32 v[86:87], v[86:87], v[132:133]
	s_nop 0
	v_pk_mul_f32 v[132:133], v[88:89], v[86:87]
	v_cvt_pk_bf16_f32 v87, v80, v81
	v_add_co_u32_e32 v80, vcc, s4, v82
	v_cvt_pk_bf16_f32 v86, v100, v101
	v_cvt_pk_bf16_f32 v88, v94, v95
	v_cvt_pk_bf16_f32 v89, v132, v133
	v_addc_co_u32_e32 v81, vcc, 0, v83, vcc
	global_store_dwordx4 v[80:81], v[86:89], off offset:2048 nt
	v_pk_fma_f32 v[80:81], v[4:5], v[124:125], v[52:53]
	s_waitcnt vmcnt(3)
; __device__ __forceinline__ unsigned cvtpk(float lo, float hi) { return pg8::cvt_pk_bf16(lo, hi); }
; __device__ __forceinline__ float bflo(unsigned w) { return __uint_as_float(w << 16); }
; __device__ __forceinline__ float bfhi(unsigned w) { return __uint_as_float(w & 0xffff0000u); }
; __device__ __forceinline__ float gelu_tanh(float x) { const float y = x * (1.0f + 0.044715f * x * x); return x * rcp(1.0f + ex2(-2.0f * 0.7978845608028654f * LOG2E * y)); }
; __device__ __forceinline__ void convgelu_phase(const bf16* __restrict__ Z, const float* __restrict__ cw, const float* __restrict__ cb, bf16* __restrict__ H, int G, const int tid_in) {
;     ...
;         for (int n4 = 0; n4 < CG_ROWS; n4 += 4) {
;             v4u gq[4], uq[4];
; #pragma unroll
;             for (int i = 0; i < 4; ++i) { gq[i] = *(const v4u*)(zp + (size_t)(n4 + i) * FF2); uq[i] = *(const v4u*)(zp + (size_t)(n4 + i) * FF2 + FF); }
; #pragma unroll
;             for (int i = 0; i < 4; ++i) { const v4u g0 = gq[i], u0 = uq[i];
;                 float o[8];
; #pragma unroll
;                 for (int e = 0; e < 4; ++e) {
;                     const float ga = bg[2 * e] + wg[0][2 * e] * bflo(g2[e]) + wg[1][2 * e] * bflo(g1[e]) + wg[2][2 * e] * bflo(g0[e]);
;                     const float gb = bg[2 * e + 1] + wg[0][2 * e + 1] * bfhi(g2[e]) + wg[1][2 * e + 1] * bfhi(g1[e]) + wg[2][2 * e + 1] * bfhi(g0[e]);
;                     const float ua = bu[2 * e] + wu[0][2 * e] * bflo(u2[e]) + wu[1][2 * e] * bflo(u1[e]) + wu[2][2 * e] * bflo(u0[e]);
;                     const float ub = bu[2 * e + 1] + wu[0][2 * e + 1] * bfhi(u2[e]) + wu[1][2 * e + 1] * bfhi(u1[e]) + wu[2][2 * e + 1] * bfhi(u0[e]);
;                     o[2 * e] = gelu_tanh(ga) * ua; o[2 * e + 1] = gelu_tanh(gb) * ub;
;                 }
;                 v4u w; w.x = cvtpk(o[0], o[1]); w.y = cvtpk(o[2], o[3]); w.z = cvtpk(o[4], o[5]); w.w = cvtpk(o[6], o[7]);
;                 *(v4u*)(hp + (size_t)(n4 + i) * FF) = w;
;                 g2 = g1; g1 = g0; u2 = u1; u1 = u0; }
;         }
;     }
	v_lshlrev_b32_e32 v94, 16, v65
	v_pk_fma_f32 v[80:81], v[20:21], v[104:105], v[80:81]
	v_lshlrev_b32_e32 v86, 16, v76
	v_and_b32_e32 v87, 0xffff0000, v76
	v_pk_fma_f32 v[80:81], v[36:37], v[86:87], v[80:81]
	v_pk_fma_f32 v[86:87], v[12:13], v[112:113], v[60:61]
	v_mul_f32_e32 v84, 0x3d372713, v80
	v_fma_f32 v84, v80, v84, 1.0
	v_mul_f32_e32 v84, v80, v84
	v_mul_f32_e32 v84, 0xc0135761, v84
	v_exp_f32_e32 v84, v84
	v_pk_fma_f32 v[86:87], v[28:29], v[120:121], v[86:87]
	v_lshlrev_b32_e32 v88, 16, v64
	v_and_b32_e32 v89, 0xffff0000, v64
	v_add_f32_e32 v84, 1.0, v84
	v_pk_fma_f32 v[86:87], v[44:45], v[88:89], v[86:87]
	v_rcp_f32_e32 v88, v84
	v_mul_f32_e32 v84, 0x3d372713, v81
	v_fma_f32 v84, v81, v84, 1.0
	v_mul_f32_e32 v84, v81, v84
	v_mul_f32_e32 v84, 0xc0135761, v84
	v_exp_f32_e32 v84, v84
	v_and_b32_e32 v95, 0xffff0000, v65
	s_mov_b64 s[4:5], 0xb000
	v_lshl_add_u64 v[116:117], v[116:117], 0, s[4:5]
	v_add_f32_e32 v84, 1.0, v84
	v_rcp_f32_e32 v89, v84
	s_mov_b64 s[4:5], 0x16000
	v_lshl_add_u64 v[118:119], v[118:119], 0, s[4:5]
	v_pk_mul_f32 v[80:81], v[80:81], v[88:89]
	s_nop 0
	v_pk_mul_f32 v[80:81], v[86:87], v[80:81]
	v_pk_fma_f32 v[86:87], v[6:7], v[108:109], v[54:55]
	v_lshlrev_b32_e32 v88, 16, v77
	v_pk_fma_f32 v[86:87], v[22:23], v[110:111], v[86:87]
	v_and_b32_e32 v89, 0xffff0000, v77
	v_pk_fma_f32 v[86:87], v[38:39], v[88:89], v[86:87]
	v_pk_fma_f32 v[88:89], v[14:15], v[106:107], v[62:63]
	v_mul_f32_e32 v84, 0x3d372713, v86
	v_fma_f32 v84, v86, v84, 1.0
	v_mul_f32_e32 v84, v86, v84
	v_mul_f32_e32 v84, 0xc0135761, v84
	v_exp_f32_e32 v84, v84
	v_pk_fma_f32 v[88:89], v[30:31], v[122:123], v[88:89]
	v_add_f32_e32 v84, 1.0, v84
	v_pk_fma_f32 v[88:89], v[46:47], v[94:95], v[88:89]
	v_rcp_f32_e32 v94, v84
	v_mul_f32_e32 v84, 0x3d372713, v87
	v_fma_f32 v84, v87, v84, 1.0
	v_mul_f32_e32 v84, v87, v84
	v_mul_f32_e32 v84, 0xc0135761, v84
	v_exp_f32_e32 v84, v84
	s_nop 0
	v_add_f32_e32 v84, 1.0, v84
	v_rcp_f32_e32 v95, v84
	s_nop 0
	v_pk_mul_f32 v[86:87], v[86:87], v[94:95]
	s_nop 0
	v_pk_mul_f32 v[88:89], v[88:89], v[86:87]
	v_pk_fma_f32 v[86:87], v[0:1], v[102:103], v[48:49]
	v_lshlrev_b32_e32 v94, 16, v66
	v_pk_fma_f32 v[86:87], v[16:17], v[90:91], v[86:87]
	v_lshlrev_b32_e32 v90, 16, v78
	v_and_b32_e32 v91, 0xffff0000, v78
	v_pk_fma_f32 v[86:87], v[32:33], v[90:91], v[86:87]
	v_pk_fma_f32 v[90:91], v[8:9], v[98:99], v[56:57]
	v_mul_f32_e32 v84, 0x3d372713, v86
	v_fma_f32 v84, v86, v84, 1.0
	v_mul_f32_e32 v84, v86, v84
	v_mul_f32_e32 v84, 0xc0135761, v84
	v_exp_f32_e32 v84, v84
	v_pk_fma_f32 v[90:91], v[24:25], v[126:127], v[90:91]
	v_and_b32_e32 v95, 0xffff0000, v66
	v_pk_fma_f32 v[90:91], v[40:41], v[94:95], v[90:91]
	v_add_f32_e32 v84, 1.0, v84
	v_rcp_f32_e32 v94, v84
	v_mul_f32_e32 v84, 0x3d372713, v87
	v_fma_f32 v84, v87, v84, 1.0
	v_mul_f32_e32 v84, v87, v84
	v_mul_f32_e32 v84, 0xc0135761, v84
	v_exp_f32_e32 v84, v84
	s_nop 0
	v_add_f32_e32 v84, 1.0, v84
	v_rcp_f32_e32 v95, v84
	s_nop 0
	v_pk_mul_f32 v[86:87], v[86:87], v[94:95]
	s_nop 0
	v_pk_mul_f32 v[90:91], v[90:91], v[86:87]
	v_pk_fma_f32 v[86:87], v[2:3], v[96:97], v[50:51]
	v_lshlrev_b32_e32 v94, 16, v79
	v_pk_fma_f32 v[86:87], v[18:19], v[128:129], v[86:87]
	v_and_b32_e32 v95, 0xffff0000, v79
	v_pk_fma_f32 v[86:87], v[34:35], v[94:95], v[86:87]
	v_lshlrev_b32_e32 v94, 16, v67
	v_mul_f32_e32 v84, 0x3d372713, v86
	v_fma_f32 v84, v86, v84, 1.0
	v_mul_f32_e32 v84, v86, v84
	v_mul_f32_e32 v84, 0xc0135761, v84
	v_exp_f32_e32 v84, v84
	v_and_b32_e32 v95, 0xffff0000, v67
	v_pk_fma_f32 v[92:93], v[42:43], v[94:95], v[92:93]
	v_add_f32_e32 v84, 1.0, v84
	v_rcp_f32_e32 v94, v84
	v_mul_f32_e32 v84, 0x3d372713, v87
	v_fma_f32 v84, v87, v84, 1.0
	v_mul_f32_e32 v84, v87, v84
	v_mul_f32_e32 v84, 0xc0135761, v84
	v_exp_f32_e32 v84, v84
	s_nop 0
	v_add_f32_e32 v84, 1.0, v84
	v_rcp_f32_e32 v95, v84
	s_nop 0
	v_pk_mul_f32 v[86:87], v[86:87], v[94:95]
	s_nop 0
	v_pk_mul_f32 v[92:93], v[92:93], v[86:87]
	v_cvt_pk_bf16_f32 v86, v80, v81
	v_add_co_u32_e32 v80, vcc, 0x37c08000, v82
	v_cvt_pk_bf16_f32 v87, v88, v89
	v_cvt_pk_bf16_f32 v88, v90, v91
	v_cvt_pk_bf16_f32 v89, v92, v93
	v_addc_co_u32_e32 v81, vcc, 0, v83, vcc
	global_store_dwordx4 v[80:81], v[86:89], off offset:1024 nt
	v_mov_b64_e32 v[82:83], v[78:79]
	v_mov_b64_e32 v[92:93], v[70:71]
	v_mov_b64_e32 v[88:89], v[74:75]
	v_mov_b64_e32 v[96:97], v[66:67]
	v_mov_b64_e32 v[86:87], v[72:73]
	v_mov_b64_e32 v[80:81], v[76:77]
	v_mov_b64_e32 v[90:91], v[68:69]
	v_mov_b64_e32 v[94:95], v[64:65]
	s_cbranch_scc0 .LBB0_102
	v_readlane_b32 s4, v255, 0
	v_readlane_b32 s5, v255, 1
	s_nop 0
	v_add_u32_e32 v138, s4, v138
	s_mov_b32 s4, 0x57fff
	v_cmp_lt_i32_e32 vcc, s4, v138
	s_or_b64 s[56:57], vcc, s[56:57]
	s_andn2_b64 exec, exec, s[56:57]
	s_cbranch_execnz .LBB0_99

; #define LAS __attribute__((address_space(3)))
; __device__ __forceinline__ void transpose_item(const float* __restrict__ W, int K, int N, bf16* __restrict__ WT, LAS float* scr, int item, int lane) {
;     const int nblk = N / 32, kb = item / nblk, nb = item % nblk, k0 = 64 * kb, n0 = 32 * nb;
;     const float* Wb = W + (size_t)k0 * N + n0; const unsigned loff = (unsigned)(lane >> 5) * (unsigned)N + (unsigned)(lane & 31);
; #pragma unroll 8
;     for (int i = 0; i < 32; ++i) { const int kk = 2 * i + (lane >> 5); scr[kk * 33 + (lane & 31)] = (Wb + (size_t)(2 * i) * N)[loff]; }
.LBB0_444:
	s_lshl_b32 s28, s11, 12
	s_add_i32 s15, s11, 2
	s_add_i32 s17, s11, 4
	v_lshl_add_u64 v[14:15], s[28:29], 2, v[10:11]
	s_lshl_b32 s28, s15, 12
	s_lshl_b32 s30, s10, 12
	s_mov_b32 s31, s29
	s_add_i32 s49, s11, 6
	v_lshl_add_u64 v[18:19], s[28:29], 2, v[10:11]
	s_lshl_b32 s28, s17, 12
	s_add_i32 s16, s10, 2
	s_add_i32 s48, s10, 4
	s_add_i32 s50, s10, 6
	s_add_i32 s51, s11, 8
	s_add_i32 s52, s10, 8
	s_add_i32 s54, s10, 10
	s_add_i32 s56, s10, 12
	s_add_i32 s58, s10, 14
	v_lshl_add_u64 v[16:17], s[30:31], 2, v[10:11]
	global_load_dword v9, v[14:15], off nt
	global_load_dword v46, v[16:17], off nt
	v_lshl_add_u64 v[14:15], s[28:29], 2, v[10:11]
	s_lshl_b32 s28, s49, 12
	s_mov_b32 s35, s29
	s_mov_b32 s37, s29
	s_mov_b32 s39, s29
	s_mov_b32 s41, s29
	s_add_i32 s53, s11, 10
	s_mov_b32 s43, s29
	s_mov_b32 s45, s29
	s_mov_b32 s47, s29
	s_lshl_b32 s34, s16, 12
	s_lshl_b32 s36, s48, 12
	s_lshl_b32 s38, s50, 12
	s_lshl_b32 s40, s52, 12
	s_lshl_b32 s42, s54, 12
	s_lshl_b32 s44, s56, 12
	s_lshl_b32 s46, s58, 12
	v_lshl_add_u64 v[16:17], s[28:29], 2, v[10:11]
	s_lshl_b32 s28, s51, 12
	s_add_i32 s55, s11, 12
	v_lshl_add_u64 v[20:21], s[34:35], 2, v[10:11]
	v_lshl_add_u64 v[22:23], s[36:37], 2, v[10:11]
	v_lshl_add_u64 v[24:25], s[38:39], 2, v[10:11]
	v_lshl_add_u64 v[26:27], s[40:41], 2, v[10:11]
	v_lshl_add_u64 v[28:29], s[42:43], 2, v[10:11]
	v_lshl_add_u64 v[30:31], s[44:45], 2, v[10:11]
	v_lshl_add_u64 v[32:33], s[46:47], 2, v[10:11]
	global_load_dword v47, v[18:19], off nt
	global_load_dword v48, v[20:21], off nt
	global_load_dword v49, v[22:23], off nt
	global_load_dword v50, v[24:25], off nt
	global_load_dword v51, v[26:27], off nt
	global_load_dword v52, v[28:29], off nt
	global_load_dword v53, v[30:31], off nt
	global_load_dword v54, v[32:33], off nt
	global_load_dword v55, v[16:17], off nt
	global_load_dword v56, v[14:15], off nt
	v_lshl_add_u64 v[14:15], s[28:29], 2, v[10:11]
	s_lshl_b32 s28, s53, 12
	s_add_i32 s57, s11, 14
	v_lshl_add_u64 v[16:17], s[28:29], 2, v[10:11]
	s_lshl_b32 s28, s55, 12
	v_lshl_add_u64 v[18:19], s[28:29], 2, v[10:11]
	s_lshl_b32 s28, s57, 12
	v_lshl_add_u64 v[20:21], s[28:29], 2, v[10:11]
	global_load_dword v57, v[20:21], off nt
	global_load_dword v58, v[18:19], off nt
	global_load_dword v59, v[16:17], off nt
	global_load_dword v60, v[14:15], off nt
	s_lshl_b32 s13, s10, 1
	s_lshl_b32 s14, s11, 1
	v_or_b32_e32 v16, s13, v1
	v_or_b32_e32 v14, s14, v0
	s_add_i32 s11, s11, 16
	s_add_i32 s10, s10, 16
	s_add_i32 s12, s12, -16
	s_lshl_b32 s13, s16, 1
	s_lshl_b32 s16, s15, 1
	s_lshl_b32 s28, s48, 1
	s_lshl_b32 s17, s17, 1
	s_lshl_b32 s30, s50, 1
	s_lshl_b32 s31, s49, 1
	s_lshl_b32 s34, s52, 1
	s_lshl_b32 s35, s51, 1
	s_lshl_b32 s36, s54, 1
	s_lshl_b32 s37, s53, 1
	s_lshl_b32 s38, s56, 1
	s_lshl_b32 s39, s55, 1
	s_lshl_b32 s40, s58, 1
	s_lshl_b32 s41, s57, 1
	v_mad_u64_u32 v[14:15], s[14:15], v14, s27, v[4:5]
	v_mad_u64_u32 v[16:17], s[14:15], v16, s27, v[4:5]
	v_or_b32_e32 v15, s13, v1
	v_or_b32_e32 v17, s16, v0
	v_or_b32_e32 v24, s28, v1
	v_or_b32_e32 v22, s17, v0
	v_or_b32_e32 v28, s30, v1
	v_or_b32_e32 v26, s31, v0
	v_or_b32_e32 v32, s34, v1
	v_or_b32_e32 v30, s35, v0
	v_or_b32_e32 v36, s36, v1
	v_or_b32_e32 v34, s37, v0
	v_or_b32_e32 v40, s38, v1
	v_or_b32_e32 v38, s39, v0
	v_or_b32_e32 v44, s40, v1
	v_or_b32_e32 v42, s41, v0
	s_cmp_lg_u32 s12, 0
	v_mad_u64_u32 v[18:19], s[14:15], v17, s27, v[4:5]
	v_mad_u64_u32 v[20:21], s[14:15], v15, s27, v[4:5]
	v_mad_u64_u32 v[22:23], s[14:15], v22, s27, v[4:5]
	v_mad_u64_u32 v[24:25], s[14:15], v24, s27, v[4:5]
	v_mad_u64_u32 v[26:27], s[14:15], v26, s27, v[4:5]
	v_mad_u64_u32 v[28:29], s[14:15], v28, s27, v[4:5]
	v_mad_u64_u32 v[30:31], s[14:15], v30, s27, v[4:5]
	v_mad_u64_u32 v[32:33], s[14:15], v32, s27, v[4:5]
	v_mad_u64_u32 v[34:35], s[14:15], v34, s27, v[4:5]
	v_mad_u64_u32 v[36:37], s[14:15], v36, s27, v[4:5]
	v_mad_u64_u32 v[38:39], s[14:15], v38, s27, v[4:5]
	v_mad_u64_u32 v[40:41], s[14:15], v40, s27, v[4:5]
	v_mad_u64_u32 v[42:43], s[14:15], v42, s27, v[4:5]
	v_mad_u64_u32 v[44:45], s[14:15], v44, s27, v[4:5]
	s_waitcnt vmcnt(0)
	ds_write_b32 v14, v9
	ds_write_b32 v16, v46
	ds_write_b32 v18, v47
	ds_write_b32 v20, v48
	ds_write_b32 v22, v56
	ds_write_b32 v24, v49
	ds_write_b32 v26, v55
	ds_write_b32 v28, v50
	ds_write_b32 v30, v60
	ds_write_b32 v32, v51
	ds_write_b32 v34, v59
	ds_write_b32 v36, v52
	ds_write_b32 v38, v58
	ds_write_b32 v40, v53
	ds_write_b32 v42, v57
	ds_write_b32 v44, v54
	s_cbranch_scc1 .LBB0_444
; #define LAS __attribute__((address_space(3)))
; __device__ __forceinline__ unsigned cvtpk(float lo, float hi) { return pg8::cvt_pk_bf16(lo, hi); }
; __device__ __forceinline__ void transpose_item(const float* __restrict__ W, int K, int N, bf16* __restrict__ WT, LAS float* scr, int item, int lane) {
;     ...
;     asm volatile("s_waitcnt lgkmcnt(0)" ::: "memory");
;     const int c = lane & 7;
; #pragma unroll
;     for (int j = 0; j < 4; ++j) { const int n = (lane >> 3) + 8 * j; const LAS float* s = scr + (8 * c) * 33 + n;
;         v4u o; o.x = cvtpk(s[0 * 33], s[1 * 33]); o.y = cvtpk(s[2 * 33], s[3 * 33]); o.z = cvtpk(s[4 * 33], s[5 * 33]); o.w = cvtpk(s[6 * 33], s[7 * 33]);
;         *(v4u*)(WT + (size_t)(n0 + n) * K + k0 + 8 * c) = o; }
;     asm volatile("s_waitcnt lgkmcnt(0)" ::: "memory");
	s_mul_i32 s11, s0, 0x1600000
	s_waitcnt lgkmcnt(0)
	s_mul_hi_i32 s10, s0, 0x1600000
	s_add_u32 s11, s86, s11
	v_readlane_b32 s12, v253, 43
	ds_read2_b32 v[18:19], v5 offset0:33 offset1:41
	ds_read2_b32 v[20:21], v5 offset1:8
	ds_read2_b32 v[22:23], v5 offset0:66 offset1:74
	ds_read2_b32 v[24:25], v5 offset0:99 offset1:107
	ds_read2_b32 v[26:27], v5 offset0:132 offset1:140
	ds_read2_b32 v[28:29], v5 offset0:165 offset1:173
	ds_read2_b32 v[30:31], v5 offset0:198 offset1:206
	ds_read2_b32 v[32:33], v5 offset0:231 offset1:239
	s_addc_u32 s12, s12, s10
	s_lshl_b32 s9, s9, 1
	s_add_u32 s10, s11, s9
	v_or_b32_e32 v9, s8, v3
	s_addc_u32 s11, s12, 0
	v_lshlrev_b32_e32 v10, 1, v6
	v_mov_b32_e32 v11, v85
	v_mul_u32_u24_e32 v9, 0x1600, v9
	v_lshl_add_u64 v[10:11], s[10:11], 0, v[10:11]
	v_lshlrev_b32_e32 v34, 1, v9
	v_mov_b32_e32 v35, v85
	s_waitcnt lgkmcnt(6)
	v_cvt_pk_bf16_f32 v14, v20, v18
	s_waitcnt lgkmcnt(4)
	v_cvt_pk_bf16_f32 v15, v22, v24
	s_waitcnt lgkmcnt(2)
	v_cvt_pk_bf16_f32 v16, v26, v28
	s_waitcnt lgkmcnt(0)
	v_cvt_pk_bf16_f32 v17, v30, v32
	v_lshl_add_u64 v[34:35], v[10:11], 0, v[34:35]
	global_store_dwordx4 v[34:35], v[14:17], off nt
	v_or_b32_e32 v9, s8, v7
	v_mul_u32_u24_e32 v9, 0x1600, v9
	v_cvt_pk_bf16_f32 v14, v21, v19
	v_cvt_pk_bf16_f32 v15, v23, v25
	v_cvt_pk_bf16_f32 v16, v27, v29
	v_cvt_pk_bf16_f32 v17, v31, v33
	ds_read2_b32 v[20:21], v5 offset0:16 offset1:24
	ds_read2_b32 v[22:23], v5 offset0:49 offset1:57
	ds_read2_b32 v[24:25], v5 offset0:82 offset1:90
	ds_read2_b32 v[26:27], v5 offset0:115 offset1:123
	ds_read2_b32 v[28:29], v5 offset0:148 offset1:156
	ds_read2_b32 v[30:31], v5 offset0:181 offset1:189
	ds_read2_b32 v[32:33], v5 offset0:214 offset1:222
	ds_read2_b32 v[34:35], v5 offset0:247 offset1:255
	v_lshlrev_b32_e32 v18, 1, v9
	v_mov_b32_e32 v19, v85
	v_or_b32_e32 v9, s8, v12
	v_lshl_add_u64 v[18:19], v[10:11], 0, v[18:19]
	v_mul_u32_u24_e32 v9, 0x1600, v9
	global_store_dwordx4 v[18:19], v[14:17], off nt
	v_lshlrev_b32_e32 v18, 1, v9
	v_mov_b32_e32 v19, v85
	v_or_b32_e32 v9, s8, v13
	s_waitcnt lgkmcnt(6)
	v_cvt_pk_bf16_f32 v14, v20, v22
	s_waitcnt lgkmcnt(4)
	v_cvt_pk_bf16_f32 v15, v24, v26
	s_waitcnt lgkmcnt(2)
	v_cvt_pk_bf16_f32 v16, v28, v30
	s_waitcnt lgkmcnt(0)
	v_cvt_pk_bf16_f32 v17, v32, v34
	v_lshl_add_u64 v[18:19], v[10:11], 0, v[18:19]
	v_mul_u32_u24_e32 v9, 0x1600, v9
	global_store_dwordx4 v[18:19], v[14:17], off nt
	v_lshlrev_b32_e32 v18, 1, v9
	v_mov_b32_e32 v19, v85
	v_cvt_pk_bf16_f32 v14, v21, v23
	v_cvt_pk_bf16_f32 v15, v25, v27
	v_cvt_pk_bf16_f32 v16, v29, v31
	v_cvt_pk_bf16_f32 v17, v33, v35
	v_lshl_add_u64 v[10:11], v[10:11], 0, v[18:19]
	global_store_dwordx4 v[10:11], v[14:17], off nt
	s_waitcnt lgkmcnt(0)
	v_readlane_b32 s50, v254, 61
	v_readlane_b32 s12, v255, 0
	s_mov_b64 s[30:31], 0
	v_readlane_b32 s51, v254, 62
	v_readlane_b32 s13, v255, 1
	s_movk_i32 s17, 0x1000

; #define LAS __attribute__((address_space(3)))
; __device__ __forceinline__ void transpose_item(const float* __restrict__ W, int K, int N, bf16* __restrict__ WT, LAS float* scr, int item, int lane) {
;     const int nblk = N / 32, kb = item / nblk, nb = item % nblk, k0 = 64 * kb, n0 = 32 * nb;
;     const float* Wb = W + (size_t)k0 * N + n0; const unsigned loff = (unsigned)(lane >> 5) * (unsigned)N + (unsigned)(lane & 31);
; #pragma unroll 8
;     for (int i = 0; i < 32; ++i) { const int kk = 2 * i + (lane >> 5); scr[kk * 33 + (lane & 31)] = (Wb + (size_t)(2 * i) * N)[loff]; }
.LBB0_448:
	s_mul_i32 s30, s10, 0x5800
	s_mul_i32 s28, s11, 0x5800
	s_mov_b32 s31, s29
	s_mov_b32 s35, s29
	s_mov_b32 s37, s29
	s_mov_b32 s39, s29
	s_mov_b32 s41, s29
	s_mov_b32 s43, s29
	s_mov_b32 s45, s29
	s_mov_b32 s17, s29
	s_mov_b32 s47, s29
	s_mov_b32 s49, s29
	s_mov_b32 s51, s29
	s_mov_b32 s53, s29
	s_mov_b32 s55, s29
	s_mov_b32 s57, s29
	v_lshl_add_u64 v[14:15], s[28:29], 2, v[10:11]
	s_add_i32 s36, s30, 0xb000
	s_add_i32 s34, s28, 0xb000
	s_add_i32 s40, s30, 0x16000
	s_add_i32 s38, s28, 0x16000
	s_add_i32 s44, s30, 0x21000
	s_add_i32 s42, s28, 0x21000
	s_add_i32 s46, s30, 0x2c000
	s_add_i32 s16, s28, 0x2c000
	s_add_i32 s50, s30, 0x37000
	s_add_i32 s48, s28, 0x37000
	s_add_i32 s54, s30, 0x42000
	s_add_i32 s52, s28, 0x42000
	s_add_i32 s56, s30, 0x4d000
	s_add_i32 s28, s28, 0x4d000
	v_lshl_add_u64 v[16:17], s[30:31], 2, v[10:11]
	v_lshl_add_u64 v[18:19], s[34:35], 2, v[10:11]
	v_lshl_add_u64 v[20:21], s[36:37], 2, v[10:11]
	v_lshl_add_u64 v[22:23], s[38:39], 2, v[10:11]
	v_lshl_add_u64 v[24:25], s[40:41], 2, v[10:11]
	v_lshl_add_u64 v[26:27], s[42:43], 2, v[10:11]
	v_lshl_add_u64 v[28:29], s[44:45], 2, v[10:11]
	v_lshl_add_u64 v[30:31], s[16:17], 2, v[10:11]
	v_lshl_add_u64 v[32:33], s[46:47], 2, v[10:11]
	v_lshl_add_u64 v[34:35], s[48:49], 2, v[10:11]
	v_lshl_add_u64 v[36:37], s[50:51], 2, v[10:11]
	v_lshl_add_u64 v[38:39], s[52:53], 2, v[10:11]
	v_lshl_add_u64 v[40:41], s[54:55], 2, v[10:11]
	v_lshl_add_u64 v[42:43], s[28:29], 2, v[10:11]
	v_lshl_add_u64 v[44:45], s[56:57], 2, v[10:11]
	global_load_dword v9, v[14:15], off nt
	global_load_dword v46, v[16:17], off nt
	global_load_dword v47, v[18:19], off nt
	global_load_dword v48, v[20:21], off nt
	global_load_dword v49, v[22:23], off nt
	global_load_dword v50, v[24:25], off nt
	global_load_dword v51, v[26:27], off nt
	global_load_dword v52, v[28:29], off nt
	global_load_dword v53, v[30:31], off nt
	global_load_dword v54, v[32:33], off nt
	global_load_dword v55, v[34:35], off nt
	global_load_dword v56, v[36:37], off nt
	global_load_dword v57, v[38:39], off nt
	global_load_dword v58, v[40:41], off nt
	global_load_dword v59, v[42:43], off nt
	global_load_dword v60, v[44:45], off nt
	s_lshl_b32 s13, s10, 1
	s_lshl_b32 s14, s11, 1
	v_or_b32_e32 v16, s13, v1
	v_or_b32_e32 v14, s14, v0
	s_add_i32 s11, s11, 16
	s_add_i32 s10, s10, 16
	s_add_i32 s12, s12, -16
	s_add_i32 s16, s13, 4
	s_add_i32 s17, s14, 4
	s_add_i32 s28, s13, 8
	s_add_i32 s30, s14, 8
	s_add_i32 s31, s13, 12
	s_add_i32 s34, s14, 12
	s_add_i32 s35, s13, 16
	s_add_i32 s36, s14, 16
	s_add_i32 s37, s13, 20
	s_add_i32 s38, s14, 20
	s_add_i32 s39, s13, 24
	s_add_i32 s40, s14, 24
	s_add_i32 s13, s13, 28
	s_add_i32 s41, s14, 28
	v_mad_u64_u32 v[14:15], s[14:15], v14, s27, v[4:5]
	v_mad_u64_u32 v[16:17], s[14:15], v16, s27, v[4:5]
	v_or_b32_e32 v15, s16, v1
	v_or_b32_e32 v17, s17, v0
	v_or_b32_e32 v24, s28, v1
	v_or_b32_e32 v22, s30, v0
	v_or_b32_e32 v28, s31, v1
	v_or_b32_e32 v26, s34, v0
	v_or_b32_e32 v32, s35, v1
	v_or_b32_e32 v30, s36, v0
	v_or_b32_e32 v36, s37, v1
	v_or_b32_e32 v34, s38, v0
	v_or_b32_e32 v40, s39, v1
	v_or_b32_e32 v38, s40, v0
	v_or_b32_e32 v44, s13, v1
	v_or_b32_e32 v42, s41, v0
	s_cmp_lg_u32 s12, 0
	v_mad_u64_u32 v[18:19], s[14:15], v17, s27, v[4:5]
	v_mad_u64_u32 v[20:21], s[14:15], v15, s27, v[4:5]
	v_mad_u64_u32 v[22:23], s[14:15], v22, s27, v[4:5]
	v_mad_u64_u32 v[24:25], s[14:15], v24, s27, v[4:5]
	v_mad_u64_u32 v[26:27], s[14:15], v26, s27, v[4:5]
	v_mad_u64_u32 v[28:29], s[14:15], v28, s27, v[4:5]
	v_mad_u64_u32 v[30:31], s[14:15], v30, s27, v[4:5]
	v_mad_u64_u32 v[32:33], s[14:15], v32, s27, v[4:5]
	v_mad_u64_u32 v[34:35], s[14:15], v34, s27, v[4:5]
	v_mad_u64_u32 v[36:37], s[14:15], v36, s27, v[4:5]
	v_mad_u64_u32 v[38:39], s[14:15], v38, s27, v[4:5]
	v_mad_u64_u32 v[40:41], s[14:15], v40, s27, v[4:5]
	v_mad_u64_u32 v[42:43], s[14:15], v42, s27, v[4:5]
	v_mad_u64_u32 v[44:45], s[14:15], v44, s27, v[4:5]
	s_waitcnt vmcnt(0)
	ds_write_b32 v14, v9
	ds_write_b32 v16, v46
	ds_write_b32 v18, v47
	ds_write_b32 v20, v48
	ds_write_b32 v22, v49
	ds_write_b32 v24, v50
	ds_write_b32 v26, v51
	ds_write_b32 v28, v52
	ds_write_b32 v30, v53
	ds_write_b32 v32, v54
	ds_write_b32 v34, v55
	ds_write_b32 v36, v56
	ds_write_b32 v38, v57
	ds_write_b32 v40, v58
	ds_write_b32 v42, v59
	ds_write_b32 v44, v60
	s_cbranch_scc1 .LBB0_448
; #define LAS __attribute__((address_space(3)))
; __device__ __forceinline__ unsigned cvtpk(float lo, float hi) { return pg8::cvt_pk_bf16(lo, hi); }
; __device__ __forceinline__ float bflo(unsigned w) { return __uint_as_float(w << 16); }
; __device__ __forceinline__ float bfhi(unsigned w) { return __uint_as_float(w & 0xffff0000u); }
; __device__ __forceinline__ void transpose_item(const float* __restrict__ W, int K, int N, bf16* __restrict__ WT, LAS float* scr, int item, int lane) {
;     ...
;     const int c = lane & 7;
; #pragma unroll
;     for (int j = 0; j < 4; ++j) { const int n = (lane >> 3) + 8 * j; const LAS float* s = scr + (8 * c) * 33 + n;
;         v4u o; o.x = cvtpk(s[0 * 33], s[1 * 33]); o.y = cvtpk(s[2 * 33], s[3 * 33]); o.z = cvtpk(s[4 * 33], s[5 * 33]); o.w = cvtpk(s[6 * 33], s[7 * 33]);
;         *(v4u*)(WT + (size_t)(n0 + n) * K + k0 + 8 * c) = o; }
; __device__ __forceinline__ void fold_rows(const bf16* __restrict__ Wt, const float* __restrict__ g, const float* __restrict__ b, float* __restrict__ c, float* __restrict__ d, int r0, int r1, int lane) {
;     ...
;         for (int j = 0; j < 4; ++j)
; #pragma unroll
;             for (int e = 0; e < 4; ++e) { const float lo = bflo(w[j][e]), hi = bfhi(w[j][e]); cs += gr[j][2 * e] * lo + gr[j][2 * e + 1] * hi; ds += br[j][2 * e] * lo + br[j][2 * e + 1] * hi; }
	v_readlane_b32 s10, v253, 44
	s_waitcnt lgkmcnt(0)
	s_add_u32 s7, s10, s7
	v_readlane_b32 s10, v253, 45
	ds_read2_b32 v[18:19], v5 offset0:33 offset1:41
	ds_read2_b32 v[20:21], v5 offset1:8
	ds_read2_b32 v[22:23], v5 offset0:66 offset1:74
	ds_read2_b32 v[24:25], v5 offset0:99 offset1:107
	ds_read2_b32 v[26:27], v5 offset0:132 offset1:140
	ds_read2_b32 v[28:29], v5 offset0:165 offset1:173
	ds_read2_b32 v[30:31], v5 offset0:198 offset1:206
	ds_read2_b32 v[32:33], v5 offset0:231 offset1:239
	s_addc_u32 s10, s10, s6
	s_and_b32 s9, 0xffff, s9
	s_lshl_b32 s6, s8, 1
	s_add_u32 s6, s7, s6
	s_addc_u32 s7, s10, 0
	v_lshlrev_b32_e32 v10, 1, v6
	v_mov_b32_e32 v11, v85
	v_or_b32_e32 v9, s9, v3
	v_lshl_add_u64 v[10:11], s[6:7], 0, v[10:11]
	v_lshlrev_b32_e32 v34, 12, v9
	v_mov_b32_e32 v35, v85
	s_waitcnt lgkmcnt(6)
	v_cvt_pk_bf16_f32 v14, v20, v18
	s_waitcnt lgkmcnt(4)
	v_cvt_pk_bf16_f32 v15, v22, v24
	s_waitcnt lgkmcnt(2)
	v_cvt_pk_bf16_f32 v16, v26, v28
	s_waitcnt lgkmcnt(0)
	v_cvt_pk_bf16_f32 v17, v30, v32
	v_lshl_add_u64 v[34:35], v[10:11], 0, v[34:35]
	global_store_dwordx4 v[34:35], v[14:17], off nt
	v_lshlrev_b32_e32 v110, 16, v14
	v_and_b32_e32 v111, 0xffff0000, v14
	v_lshlrev_b32_e32 v112, 16, v15
	v_and_b32_e32 v113, 0xffff0000, v15
	v_lshlrev_b32_e32 v114, 16, v16
	v_and_b32_e32 v115, 0xffff0000, v16
	v_lshlrev_b32_e32 v116, 16, v17
	v_and_b32_e32 v117, 0xffff0000, v17
	v_mul_f32_e32 v118, v94, v110
	v_mul_f32_e32 v119, v102, v110
	v_fmac_f32_e32 v118, v95, v111
	v_fmac_f32_e32 v119, v103, v111
	v_fmac_f32_e32 v118, v96, v112
	v_fmac_f32_e32 v119, v104, v112
	v_fmac_f32_e32 v118, v97, v113
	v_fmac_f32_e32 v119, v105, v113
	v_fmac_f32_e32 v118, v98, v114
	v_fmac_f32_e32 v119, v106, v114
	v_fmac_f32_e32 v118, v99, v115
	v_fmac_f32_e32 v119, v107, v115
	v_fmac_f32_e32 v118, v100, v116
	v_fmac_f32_e32 v119, v108, v116
	v_fmac_f32_e32 v118, v101, v117
	v_fmac_f32_e32 v119, v109, v117
	v_or_b32_e32 v9, s9, v7
	v_lshlrev_b32_e32 v18, 12, v9
	v_cvt_pk_bf16_f32 v14, v21, v19
	v_cvt_pk_bf16_f32 v15, v23, v25
	v_cvt_pk_bf16_f32 v16, v27, v29
	v_cvt_pk_bf16_f32 v17, v31, v33
	ds_read2_b32 v[20:21], v5 offset0:49 offset1:57
	ds_read2_b32 v[22:23], v5 offset0:16 offset1:24
	ds_read2_b32 v[24:25], v5 offset0:82 offset1:90
	ds_read2_b32 v[26:27], v5 offset0:115 offset1:123
	ds_read2_b32 v[28:29], v5 offset0:148 offset1:156
	ds_read2_b32 v[30:31], v5 offset0:181 offset1:189
	ds_read2_b32 v[32:33], v5 offset0:214 offset1:222
	ds_read2_b32 v[34:35], v5 offset0:247 offset1:255
	v_mov_b32_e32 v19, v85
	v_lshl_add_u64 v[18:19], v[10:11], 0, v[18:19]
	v_or_b32_e32 v9, s9, v12
	global_store_dwordx4 v[18:19], v[14:17], off nt
	v_lshlrev_b32_e32 v110, 16, v14
	v_and_b32_e32 v111, 0xffff0000, v14
	v_lshlrev_b32_e32 v112, 16, v15
	v_and_b32_e32 v113, 0xffff0000, v15
	v_lshlrev_b32_e32 v114, 16, v16
	v_and_b32_e32 v115, 0xffff0000, v16
	v_lshlrev_b32_e32 v116, 16, v17
	v_and_b32_e32 v117, 0xffff0000, v17
	v_mul_f32_e32 v120, v94, v110
	v_mul_f32_e32 v121, v102, v110
	v_fmac_f32_e32 v120, v95, v111
	v_fmac_f32_e32 v121, v103, v111
	v_fmac_f32_e32 v120, v96, v112
	v_fmac_f32_e32 v121, v104, v112
	v_fmac_f32_e32 v120, v97, v113
	v_fmac_f32_e32 v121, v105, v113
	v_fmac_f32_e32 v120, v98, v114
	v_fmac_f32_e32 v121, v106, v114
	v_fmac_f32_e32 v120, v99, v115
	v_fmac_f32_e32 v121, v107, v115
	v_fmac_f32_e32 v120, v100, v116
	v_fmac_f32_e32 v121, v108, v116
	v_fmac_f32_e32 v120, v101, v117
	v_fmac_f32_e32 v121, v109, v117
	v_lshlrev_b32_e32 v18, 12, v9
	v_mov_b32_e32 v19, v85
	s_waitcnt lgkmcnt(6)
	v_cvt_pk_bf16_f32 v14, v22, v20
	s_waitcnt lgkmcnt(4)
	v_cvt_pk_bf16_f32 v15, v24, v26
	s_waitcnt lgkmcnt(2)
	v_cvt_pk_bf16_f32 v16, v28, v30
	s_waitcnt lgkmcnt(0)
; #define LAS __attribute__((address_space(3)))
; __device__ __forceinline__ unsigned cvtpk(float lo, float hi) { return pg8::cvt_pk_bf16(lo, hi); }
; __device__ __forceinline__ void transpose_item(const float* __restrict__ W, int K, int N, bf16* __restrict__ WT, LAS float* scr, int item, int lane) {
;     ...
;     for (int j = 0; j < 4; ++j) { const int n = (lane >> 3) + 8 * j; const LAS float* s = scr + (8 * c) * 33 + n;
;         v4u o; o.x = cvtpk(s[0 * 33], s[1 * 33]); o.y = cvtpk(s[2 * 33], s[3 * 33]); o.z = cvtpk(s[4 * 33], s[5 * 33]); o.w = cvtpk(s[6 * 33], s[7 * 33]);
;         *(v4u*)(WT + (size_t)(n0 + n) * K + k0 + 8 * c) = o; }
;     asm volatile("s_waitcnt lgkmcnt(0)" ::: "memory");
; __device__ __forceinline__ void fold_rows(const bf16* __restrict__ Wt, const float* __restrict__ g, const float* __restrict__ b, float* __restrict__ c, float* __restrict__ d, int r0, int r1, int lane) {
;     ...
;         cs = wave_sum(cs); ds = wave_sum(ds);
;         if (lane == 0) { c[r] = cs; d[r] = ds; } }
	v_cvt_pk_bf16_f32 v17, v32, v34
	v_lshl_add_u64 v[18:19], v[10:11], 0, v[18:19]
	v_or_b32_e32 v9, s9, v13
	global_store_dwordx4 v[18:19], v[14:17], off nt
	v_lshlrev_b32_e32 v110, 16, v14
	v_and_b32_e32 v111, 0xffff0000, v14
	v_lshlrev_b32_e32 v112, 16, v15
	v_and_b32_e32 v113, 0xffff0000, v15
	v_lshlrev_b32_e32 v114, 16, v16
	v_and_b32_e32 v115, 0xffff0000, v16
	v_lshlrev_b32_e32 v116, 16, v17
	v_and_b32_e32 v117, 0xffff0000, v17
	v_mul_f32_e32 v122, v94, v110
	v_mul_f32_e32 v123, v102, v110
	v_fmac_f32_e32 v122, v95, v111
	v_fmac_f32_e32 v123, v103, v111
	v_fmac_f32_e32 v122, v96, v112
	v_fmac_f32_e32 v123, v104, v112
	v_fmac_f32_e32 v122, v97, v113
	v_fmac_f32_e32 v123, v105, v113
	v_fmac_f32_e32 v122, v98, v114
	v_fmac_f32_e32 v123, v106, v114
	v_fmac_f32_e32 v122, v99, v115
	v_fmac_f32_e32 v123, v107, v115
	v_fmac_f32_e32 v122, v100, v116
	v_fmac_f32_e32 v123, v108, v116
	v_fmac_f32_e32 v122, v101, v117
	v_fmac_f32_e32 v123, v109, v117
	v_lshlrev_b32_e32 v18, 12, v9
	v_mov_b32_e32 v19, v85
	v_cvt_pk_bf16_f32 v14, v23, v21
	v_cvt_pk_bf16_f32 v15, v25, v27
	v_cvt_pk_bf16_f32 v16, v29, v31
	v_cvt_pk_bf16_f32 v17, v33, v35
	v_lshl_add_u64 v[10:11], v[10:11], 0, v[18:19]
	global_store_dwordx4 v[10:11], v[14:17], off nt
	v_lshlrev_b32_e32 v110, 16, v14
	v_and_b32_e32 v111, 0xffff0000, v14
	v_lshlrev_b32_e32 v112, 16, v15
	v_and_b32_e32 v113, 0xffff0000, v15
	v_lshlrev_b32_e32 v114, 16, v16
	v_and_b32_e32 v115, 0xffff0000, v16
	v_lshlrev_b32_e32 v116, 16, v17
	v_and_b32_e32 v117, 0xffff0000, v17
	v_mul_f32_e32 v124, v94, v110
	v_mul_f32_e32 v125, v102, v110
	v_fmac_f32_e32 v124, v95, v111
	v_fmac_f32_e32 v125, v103, v111
	v_fmac_f32_e32 v124, v96, v112
	v_fmac_f32_e32 v125, v104, v112
	v_fmac_f32_e32 v124, v97, v113
	v_fmac_f32_e32 v125, v105, v113
	v_fmac_f32_e32 v124, v98, v114
	v_fmac_f32_e32 v125, v106, v114
	v_fmac_f32_e32 v124, v99, v115
	v_fmac_f32_e32 v125, v107, v115
	v_fmac_f32_e32 v124, v100, v116
	v_fmac_f32_e32 v125, v108, v116
	v_fmac_f32_e32 v124, v101, v117
	v_fmac_f32_e32 v125, v109, v117
	v_add_f32_dpp v118, v118, v118 quad_perm:[1,0,3,2] row_mask:0xf bank_mask:0xf
	v_add_f32_dpp v119, v119, v119 quad_perm:[1,0,3,2] row_mask:0xf bank_mask:0xf
	v_add_f32_dpp v120, v120, v120 quad_perm:[1,0,3,2] row_mask:0xf bank_mask:0xf
	v_add_f32_dpp v121, v121, v121 quad_perm:[1,0,3,2] row_mask:0xf bank_mask:0xf
	v_add_f32_dpp v122, v122, v122 quad_perm:[1,0,3,2] row_mask:0xf bank_mask:0xf
	v_add_f32_dpp v123, v123, v123 quad_perm:[1,0,3,2] row_mask:0xf bank_mask:0xf
	v_add_f32_dpp v124, v124, v124 quad_perm:[1,0,3,2] row_mask:0xf bank_mask:0xf
	v_add_f32_dpp v125, v125, v125 quad_perm:[1,0,3,2] row_mask:0xf bank_mask:0xf
	v_add_f32_dpp v118, v118, v118 quad_perm:[2,3,0,1] row_mask:0xf bank_mask:0xf
	v_add_f32_dpp v119, v119, v119 quad_perm:[2,3,0,1] row_mask:0xf bank_mask:0xf
	v_add_f32_dpp v120, v120, v120 quad_perm:[2,3,0,1] row_mask:0xf bank_mask:0xf
	v_add_f32_dpp v121, v121, v121 quad_perm:[2,3,0,1] row_mask:0xf bank_mask:0xf
	v_add_f32_dpp v122, v122, v122 quad_perm:[2,3,0,1] row_mask:0xf bank_mask:0xf
	v_add_f32_dpp v123, v123, v123 quad_perm:[2,3,0,1] row_mask:0xf bank_mask:0xf
	v_add_f32_dpp v124, v124, v124 quad_perm:[2,3,0,1] row_mask:0xf bank_mask:0xf
	v_add_f32_dpp v125, v125, v125 quad_perm:[2,3,0,1] row_mask:0xf bank_mask:0xf
	v_add_f32_dpp v118, v118, v118 row_half_mirror row_mask:0xf bank_mask:0xf
	v_add_f32_dpp v119, v119, v119 row_half_mirror row_mask:0xf bank_mask:0xf
	v_add_f32_dpp v120, v120, v120 row_half_mirror row_mask:0xf bank_mask:0xf
	v_add_f32_dpp v121, v121, v121 row_half_mirror row_mask:0xf bank_mask:0xf
	v_add_f32_dpp v122, v122, v122 row_half_mirror row_mask:0xf bank_mask:0xf
	v_add_f32_dpp v123, v123, v123 row_half_mirror row_mask:0xf bank_mask:0xf
	v_add_f32_dpp v124, v124, v124 row_half_mirror row_mask:0xf bank_mask:0xf
	v_add_f32_dpp v125, v125, v125 row_half_mirror row_mask:0xf bank_mask:0xf
	v_cmp_eq_u32_e32 vcc, 0, v6
	s_and_saveexec_b64 s[36:37], vcc
	s_lshl_b32 s100, s0, 5
	s_lshr_b32 s101, s8, 6
	s_add_i32 s100, s100, s101
	s_mul_i32 s100, s100, 0x2c00
	s_and_b32 s101, s9, 0xffff
	s_add_i32 s100, s100, s101
	s_lshl_b32 s100, s100, 3
	s_add_u32 s38, s20, 0x1a000000
	s_addc_u32 s39, s21, 0
	v_lshlrev_b32_e32 v126, 3, v3
	v_add_u32_e32 v126, s100, v126
	global_store_dwordx2 v126, v[118:119], s[38:39]
	global_store_dwordx2 v126, v[120:121], s[38:39] offset:64
	global_store_dwordx2 v126, v[122:123], s[38:39] offset:128
	global_store_dwordx2 v126, v[124:125], s[38:39] offset:192
	s_or_b64 exec, exec, s[36:37]
	s_waitcnt lgkmcnt(0)
	v_readlane_b32 s50, v254, 61
	v_readlane_b32 s12, v255, 0
	s_movk_i32 s17, 0x1000
	v_readlane_b32 s51, v254, 62
	v_readlane_b32 s13, v255, 1

; #define LAS __attribute__((address_space(3)))
; __device__ __forceinline__ void transpose_item(const float* __restrict__ W, int K, int N, bf16* __restrict__ WT, LAS float* scr, int item, int lane) {
;     const int nblk = N / 32, kb = item / nblk, nb = item % nblk, k0 = 64 * kb, n0 = 32 * nb;
;     const float* Wb = W + (size_t)k0 * N + n0; const unsigned loff = (unsigned)(lane >> 5) * (unsigned)N + (unsigned)(lane & 31);
; #pragma unroll 8
;     for (int i = 0; i < 32; ++i) { const int kk = 2 * i + (lane >> 5); scr[kk * 33 + (lane & 31)] = (Wb + (size_t)(2 * i) * N)[loff]; }
.LBB0_453:
	s_lshl_b32 s28, s8, 12
	s_add_i32 s12, s8, 2
	s_add_i32 s46, s8, 4
	v_lshl_add_u64 v[14:15], s[28:29], 2, v[10:11]
	s_lshl_b32 s28, s12, 12
	s_lshl_b32 s34, s7, 12
	s_mov_b32 s35, s29
	s_add_i32 s48, s8, 6
	v_lshl_add_u64 v[18:19], s[28:29], 2, v[10:11]
	s_lshl_b32 s28, s46, 12
	s_add_i32 s13, s7, 2
	s_add_i32 s47, s7, 4
	s_add_i32 s49, s7, 6
	s_add_i32 s50, s8, 8
	s_add_i32 s51, s7, 8
	s_add_i32 s53, s7, 10
	s_add_i32 s55, s7, 12
	s_add_i32 s57, s7, 14
	v_lshl_add_u64 v[16:17], s[34:35], 2, v[10:11]
	global_load_dword v9, v[14:15], off nt
	global_load_dword v46, v[16:17], off nt
	v_lshl_add_u64 v[14:15], s[28:29], 2, v[10:11]
	s_lshl_b32 s28, s48, 12
	s_mov_b32 s37, s29
	s_mov_b32 s39, s29
	s_mov_b32 s41, s29
	s_mov_b32 s15, s29
	s_add_i32 s52, s8, 10
	s_mov_b32 s17, s29
	s_mov_b32 s43, s29
	s_mov_b32 s45, s29
	s_lshl_b32 s36, s13, 12
	s_lshl_b32 s38, s47, 12
	s_lshl_b32 s40, s49, 12
	s_lshl_b32 s14, s51, 12
	s_lshl_b32 s16, s53, 12
	s_lshl_b32 s42, s55, 12
	s_lshl_b32 s44, s57, 12
	v_lshl_add_u64 v[16:17], s[28:29], 2, v[10:11]
	s_lshl_b32 s28, s50, 12
	s_add_i32 s54, s8, 12
	v_lshl_add_u64 v[20:21], s[36:37], 2, v[10:11]
	v_lshl_add_u64 v[22:23], s[38:39], 2, v[10:11]
	v_lshl_add_u64 v[24:25], s[40:41], 2, v[10:11]
	v_lshl_add_u64 v[26:27], s[14:15], 2, v[10:11]
	v_lshl_add_u64 v[28:29], s[16:17], 2, v[10:11]
	v_lshl_add_u64 v[30:31], s[42:43], 2, v[10:11]
	v_lshl_add_u64 v[32:33], s[44:45], 2, v[10:11]
	global_load_dword v47, v[18:19], off nt
	global_load_dword v48, v[20:21], off nt
	global_load_dword v49, v[22:23], off nt
	global_load_dword v50, v[24:25], off nt
	global_load_dword v51, v[26:27], off nt
	global_load_dword v52, v[28:29], off nt
	global_load_dword v53, v[30:31], off nt
	global_load_dword v54, v[32:33], off nt
	global_load_dword v55, v[16:17], off nt
	global_load_dword v56, v[14:15], off nt
	v_lshl_add_u64 v[14:15], s[28:29], 2, v[10:11]
	s_lshl_b32 s28, s52, 12
	s_add_i32 s56, s8, 14
	v_lshl_add_u64 v[16:17], s[28:29], 2, v[10:11]
	s_lshl_b32 s28, s54, 12
	v_lshl_add_u64 v[18:19], s[28:29], 2, v[10:11]
	s_lshl_b32 s28, s56, 12
	v_lshl_add_u64 v[20:21], s[28:29], 2, v[10:11]
	global_load_dword v57, v[20:21], off nt
	global_load_dword v58, v[18:19], off nt
	global_load_dword v59, v[16:17], off nt
	global_load_dword v60, v[14:15], off nt
	s_lshl_b32 s10, s7, 1
	s_lshl_b32 s11, s8, 1
	v_or_b32_e32 v16, s10, v1
	v_or_b32_e32 v14, s11, v0
	s_add_i32 s8, s8, 16
	s_add_i32 s7, s7, 16
	s_add_i32 s9, s9, -16
	s_lshl_b32 s13, s13, 1
	s_lshl_b32 s12, s12, 1
	s_lshl_b32 s14, s47, 1
	s_lshl_b32 s15, s46, 1
	s_lshl_b32 s16, s49, 1
	s_lshl_b32 s17, s48, 1
	s_lshl_b32 s28, s51, 1
	s_lshl_b32 s34, s50, 1
	s_lshl_b32 s35, s53, 1
	s_lshl_b32 s36, s52, 1
	s_lshl_b32 s37, s55, 1
	s_lshl_b32 s38, s54, 1
	s_lshl_b32 s39, s57, 1
	s_lshl_b32 s40, s56, 1
	v_mad_u64_u32 v[14:15], s[10:11], v14, s27, v[4:5]
	v_mad_u64_u32 v[16:17], s[10:11], v16, s27, v[4:5]
	v_or_b32_e32 v15, s13, v1
	v_or_b32_e32 v17, s12, v0
	v_or_b32_e32 v24, s14, v1
	v_or_b32_e32 v22, s15, v0
	v_or_b32_e32 v28, s16, v1
	v_or_b32_e32 v26, s17, v0
	v_or_b32_e32 v32, s28, v1
	v_or_b32_e32 v30, s34, v0
	v_or_b32_e32 v36, s35, v1
	v_or_b32_e32 v34, s36, v0
	v_or_b32_e32 v40, s37, v1
	v_or_b32_e32 v38, s38, v0
	v_or_b32_e32 v44, s39, v1
	v_or_b32_e32 v42, s40, v0
	s_cmp_lg_u32 s9, 0
	v_mad_u64_u32 v[18:19], s[10:11], v17, s27, v[4:5]
	v_mad_u64_u32 v[20:21], s[10:11], v15, s27, v[4:5]
	v_mad_u64_u32 v[22:23], s[10:11], v22, s27, v[4:5]
	v_mad_u64_u32 v[24:25], s[10:11], v24, s27, v[4:5]
	v_mad_u64_u32 v[26:27], s[10:11], v26, s27, v[4:5]
	v_mad_u64_u32 v[28:29], s[10:11], v28, s27, v[4:5]
	v_mad_u64_u32 v[30:31], s[10:11], v30, s27, v[4:5]
	v_mad_u64_u32 v[32:33], s[10:11], v32, s27, v[4:5]
	v_mad_u64_u32 v[34:35], s[10:11], v34, s27, v[4:5]
	v_mad_u64_u32 v[36:37], s[10:11], v36, s27, v[4:5]
	v_mad_u64_u32 v[38:39], s[10:11], v38, s27, v[4:5]
	v_mad_u64_u32 v[40:41], s[10:11], v40, s27, v[4:5]
	v_mad_u64_u32 v[42:43], s[10:11], v42, s27, v[4:5]
	v_mad_u64_u32 v[44:45], s[10:11], v44, s27, v[4:5]
	s_waitcnt vmcnt(0)
	ds_write_b32 v14, v9
	ds_write_b32 v16, v46
	ds_write_b32 v18, v47
	ds_write_b32 v20, v48
	ds_write_b32 v22, v56
	ds_write_b32 v24, v49
	ds_write_b32 v26, v55
	ds_write_b32 v28, v50
	ds_write_b32 v30, v60
	ds_write_b32 v32, v51
	ds_write_b32 v34, v59
	ds_write_b32 v36, v52
	ds_write_b32 v38, v58
	ds_write_b32 v40, v53
	ds_write_b32 v42, v57
	ds_write_b32 v44, v54
	s_cbranch_scc1 .LBB0_453
; #define LAS __attribute__((address_space(3)))
; __device__ __forceinline__ unsigned cvtpk(float lo, float hi) { return pg8::cvt_pk_bf16(lo, hi); }
; __device__ __forceinline__ void transpose_item(const float* __restrict__ W, int K, int N, bf16* __restrict__ WT, LAS float* scr, int item, int lane) {
;     ...
;     asm volatile("s_waitcnt lgkmcnt(0)" ::: "memory");
;     const int c = lane & 7;
; #pragma unroll
;     for (int j = 0; j < 4; ++j) { const int n = (lane >> 3) + 8 * j; const LAS float* s = scr + (8 * c) * 33 + n;
;         v4u o; o.x = cvtpk(s[0 * 33], s[1 * 33]); o.y = cvtpk(s[2 * 33], s[3 * 33]); o.z = cvtpk(s[4 * 33], s[5 * 33]); o.w = cvtpk(s[6 * 33], s[7 * 33]);
;         *(v4u*)(WT + (size_t)(n0 + n) * K + k0 + 8 * c) = o; }
;     asm volatile("s_waitcnt lgkmcnt(0)" ::: "memory");
	s_lshl_b64 s[8:9], s[30:31], 1
	v_readlane_b32 s7, v253, 46
	s_waitcnt lgkmcnt(0)
	s_add_u32 s7, s7, s8
	v_readlane_b32 s8, v253, 47
	ds_read2_b32 v[18:19], v5 offset0:33 offset1:41
	ds_read2_b32 v[20:21], v5 offset1:8
	ds_read2_b32 v[22:23], v5 offset0:66 offset1:74
	ds_read2_b32 v[24:25], v5 offset0:99 offset1:107
	ds_read2_b32 v[26:27], v5 offset0:132 offset1:140
	ds_read2_b32 v[28:29], v5 offset0:165 offset1:173
	ds_read2_b32 v[30:31], v5 offset0:198 offset1:206
	ds_read2_b32 v[32:33], v5 offset0:231 offset1:239
	s_addc_u32 s8, s8, s9
	s_lshl_b32 s6, s6, 1
	s_add_u32 s6, s7, s6
	s_addc_u32 s7, s8, 0
	v_lshlrev_b32_e32 v10, 1, v6
	v_mov_b32_e32 v11, v85
	v_or_b32_e32 v9, s1, v3
	v_lshl_add_u64 v[10:11], s[6:7], 0, v[10:11]
	v_lshlrev_b32_e32 v34, 12, v9
	v_mov_b32_e32 v35, v85
	s_waitcnt lgkmcnt(6)
	v_cvt_pk_bf16_f32 v14, v20, v18
	s_waitcnt lgkmcnt(4)
	v_cvt_pk_bf16_f32 v15, v22, v24
	s_waitcnt lgkmcnt(2)
	v_cvt_pk_bf16_f32 v16, v26, v28
	s_waitcnt lgkmcnt(0)
	v_cvt_pk_bf16_f32 v17, v30, v32
	v_lshl_add_u64 v[34:35], v[10:11], 0, v[34:35]
	global_store_dwordx4 v[34:35], v[14:17], off nt
	v_or_b32_e32 v9, s1, v7
	v_lshlrev_b32_e32 v18, 12, v9
	v_cvt_pk_bf16_f32 v14, v21, v19
	v_cvt_pk_bf16_f32 v15, v23, v25
	v_cvt_pk_bf16_f32 v16, v27, v29
	v_cvt_pk_bf16_f32 v17, v31, v33
	ds_read2_b32 v[20:21], v5 offset0:49 offset1:57
	ds_read2_b32 v[22:23], v5 offset0:16 offset1:24
	ds_read2_b32 v[24:25], v5 offset0:82 offset1:90
	ds_read2_b32 v[26:27], v5 offset0:115 offset1:123
	ds_read2_b32 v[28:29], v5 offset0:148 offset1:156
	ds_read2_b32 v[30:31], v5 offset0:181 offset1:189
	ds_read2_b32 v[32:33], v5 offset0:214 offset1:222
	ds_read2_b32 v[34:35], v5 offset0:247 offset1:255
	v_mov_b32_e32 v19, v85
	v_lshl_add_u64 v[18:19], v[10:11], 0, v[18:19]
	v_or_b32_e32 v9, s1, v12
	global_store_dwordx4 v[18:19], v[14:17], off nt
	v_lshlrev_b32_e32 v18, 12, v9
	v_mov_b32_e32 v19, v85
	s_waitcnt lgkmcnt(6)
	v_cvt_pk_bf16_f32 v14, v22, v20
	s_waitcnt lgkmcnt(4)
	v_cvt_pk_bf16_f32 v15, v24, v26
	s_waitcnt lgkmcnt(2)
	v_cvt_pk_bf16_f32 v16, v28, v30
	s_waitcnt lgkmcnt(0)
	v_cvt_pk_bf16_f32 v17, v32, v34
	v_lshl_add_u64 v[18:19], v[10:11], 0, v[18:19]
	v_or_b32_e32 v9, s1, v13
	global_store_dwordx4 v[18:19], v[14:17], off nt
	v_lshlrev_b32_e32 v18, 12, v9
	v_mov_b32_e32 v19, v85
	v_cvt_pk_bf16_f32 v14, v23, v21
	v_cvt_pk_bf16_f32 v15, v25, v27
	v_cvt_pk_bf16_f32 v16, v29, v31
	v_cvt_pk_bf16_f32 v17, v33, v35
	v_lshl_add_u64 v[10:11], v[10:11], 0, v[18:19]
	global_store_dwordx4 v[10:11], v[14:17], off nt
	s_waitcnt lgkmcnt(0)
	v_readlane_b32 s50, v254, 61
	v_readlane_b32 s12, v255, 0
	s_movk_i32 s17, 0x1000
	v_readlane_b32 s51, v254, 62
	v_readlane_b32 s13, v255, 1

; #define LAS __attribute__((address_space(3)))
; __device__ __forceinline__ void transpose_item(const float* __restrict__ W, int K, int N, bf16* __restrict__ WT, LAS float* scr, int item, int lane) {
;     const int nblk = N / 32, kb = item / nblk, nb = item % nblk, k0 = 64 * kb, n0 = 32 * nb;
;     const float* Wb = W + (size_t)k0 * N + n0; const unsigned loff = (unsigned)(lane >> 5) * (unsigned)N + (unsigned)(lane & 31);
; #pragma unroll 8
;     for (int i = 0; i < 32; ++i) { const int kk = 2 * i + (lane >> 5); scr[kk * 33 + (lane & 31)] = (Wb + (size_t)(2 * i) * N)[loff]; }
.LBB0_457:
	s_mul_i32 s36, s1, 0x2800
	s_mul_i32 s28, s5, 0x2800
	s_mov_b32 s37, s29
	s_mov_b32 s39, s29
	s_mov_b32 s41, s29
	s_mov_b32 s43, s29
	s_mov_b32 s45, s29
	s_mov_b32 s47, s29
	s_mov_b32 s49, s29
	s_mov_b32 s11, s29
	s_mov_b32 s13, s29
	s_mov_b32 s15, s29
	s_mov_b32 s17, s29
	s_mov_b32 s51, s29
	s_mov_b32 s53, s29
	s_mov_b32 s55, s29
	v_lshl_add_u64 v[14:15], s[28:29], 2, v[10:11]
	s_add_i32 s40, s36, 0x5000
	s_add_i32 s38, s28, 0x5000
	s_add_i32 s44, s36, 0xa000
	s_add_i32 s42, s28, 0xa000
	s_add_i32 s48, s36, 0xf000
	s_add_i32 s46, s28, 0xf000
	s_add_i32 s12, s36, 0x14000
	s_add_i32 s10, s28, 0x14000
	s_add_i32 s16, s36, 0x19000
	s_add_i32 s14, s28, 0x19000
	s_add_i32 s52, s36, 0x1e000
	s_add_i32 s50, s28, 0x1e000
	s_add_i32 s54, s36, 0x23000
	s_add_i32 s28, s28, 0x23000
	v_lshl_add_u64 v[16:17], s[36:37], 2, v[10:11]
	v_lshl_add_u64 v[18:19], s[38:39], 2, v[10:11]
	v_lshl_add_u64 v[20:21], s[40:41], 2, v[10:11]
	v_lshl_add_u64 v[22:23], s[42:43], 2, v[10:11]
	v_lshl_add_u64 v[24:25], s[44:45], 2, v[10:11]
	v_lshl_add_u64 v[26:27], s[46:47], 2, v[10:11]
	v_lshl_add_u64 v[28:29], s[48:49], 2, v[10:11]
	v_lshl_add_u64 v[30:31], s[10:11], 2, v[10:11]
	v_lshl_add_u64 v[32:33], s[12:13], 2, v[10:11]
	v_lshl_add_u64 v[34:35], s[14:15], 2, v[10:11]
	v_lshl_add_u64 v[36:37], s[16:17], 2, v[10:11]
	v_lshl_add_u64 v[38:39], s[50:51], 2, v[10:11]
	v_lshl_add_u64 v[40:41], s[52:53], 2, v[10:11]
	v_lshl_add_u64 v[42:43], s[28:29], 2, v[10:11]
	v_lshl_add_u64 v[44:45], s[54:55], 2, v[10:11]
	global_load_dword v9, v[14:15], off nt
	global_load_dword v46, v[16:17], off nt
	global_load_dword v47, v[18:19], off nt
	global_load_dword v48, v[20:21], off nt
	global_load_dword v49, v[22:23], off nt
	global_load_dword v50, v[24:25], off nt
	global_load_dword v51, v[26:27], off nt
	global_load_dword v52, v[28:29], off nt
	global_load_dword v53, v[30:31], off nt
	global_load_dword v54, v[32:33], off nt
	global_load_dword v55, v[34:35], off nt
	global_load_dword v56, v[36:37], off nt
	global_load_dword v57, v[38:39], off nt
	global_load_dword v58, v[40:41], off nt
	global_load_dword v59, v[42:43], off nt
	global_load_dword v60, v[44:45], off nt
	s_lshl_b32 s7, s1, 1
	s_lshl_b32 s8, s5, 1
	v_or_b32_e32 v16, s7, v1
	v_or_b32_e32 v14, s8, v0
	s_add_i32 s5, s5, 16
	s_add_i32 s1, s1, 16
	s_add_i32 s6, s6, -16
	s_add_i32 s10, s7, 4
	s_add_i32 s11, s8, 4
	s_add_i32 s12, s7, 8
	s_add_i32 s13, s8, 8
	s_add_i32 s14, s7, 12
	s_add_i32 s15, s8, 12
	s_add_i32 s16, s7, 16
	s_add_i32 s17, s8, 16
	s_add_i32 s28, s7, 20
	s_add_i32 s31, s8, 20
	s_add_i32 s36, s7, 24
	s_add_i32 s37, s8, 24
	s_add_i32 s7, s7, 28
	s_add_i32 s38, s8, 28
	v_mad_u64_u32 v[14:15], s[8:9], v14, s27, v[4:5]
	v_mad_u64_u32 v[16:17], s[8:9], v16, s27, v[4:5]
	v_or_b32_e32 v15, s10, v1
	v_or_b32_e32 v17, s11, v0
	v_or_b32_e32 v24, s12, v1
	v_or_b32_e32 v22, s13, v0
	v_or_b32_e32 v28, s14, v1
	v_or_b32_e32 v26, s15, v0
	v_or_b32_e32 v32, s16, v1
	v_or_b32_e32 v30, s17, v0
	v_or_b32_e32 v36, s28, v1
	v_or_b32_e32 v34, s31, v0
	v_or_b32_e32 v40, s36, v1
	v_or_b32_e32 v38, s37, v0
	v_or_b32_e32 v44, s7, v1
	v_or_b32_e32 v42, s38, v0
	s_cmp_lg_u32 s6, 0
	v_mad_u64_u32 v[18:19], s[8:9], v17, s27, v[4:5]
	v_mad_u64_u32 v[20:21], s[8:9], v15, s27, v[4:5]
	v_mad_u64_u32 v[22:23], s[8:9], v22, s27, v[4:5]
	v_mad_u64_u32 v[24:25], s[8:9], v24, s27, v[4:5]
	v_mad_u64_u32 v[26:27], s[8:9], v26, s27, v[4:5]
	v_mad_u64_u32 v[28:29], s[8:9], v28, s27, v[4:5]
	v_mad_u64_u32 v[30:31], s[8:9], v30, s27, v[4:5]
	v_mad_u64_u32 v[32:33], s[8:9], v32, s27, v[4:5]
	v_mad_u64_u32 v[34:35], s[8:9], v34, s27, v[4:5]
	v_mad_u64_u32 v[36:37], s[8:9], v36, s27, v[4:5]
	v_mad_u64_u32 v[38:39], s[8:9], v38, s27, v[4:5]
	v_mad_u64_u32 v[40:41], s[8:9], v40, s27, v[4:5]
	v_mad_u64_u32 v[42:43], s[8:9], v42, s27, v[4:5]
	v_mad_u64_u32 v[44:45], s[8:9], v44, s27, v[4:5]
	s_waitcnt vmcnt(0)
	ds_write_b32 v14, v9
	ds_write_b32 v16, v46
	ds_write_b32 v18, v47
	ds_write_b32 v20, v48
	ds_write_b32 v22, v49
	ds_write_b32 v24, v50
	ds_write_b32 v26, v51
	ds_write_b32 v28, v52
	ds_write_b32 v30, v53
	ds_write_b32 v32, v54
	ds_write_b32 v34, v55
	ds_write_b32 v36, v56
	ds_write_b32 v38, v57
	ds_write_b32 v40, v58
	ds_write_b32 v42, v59
	ds_write_b32 v44, v60
	s_cbranch_scc1 .LBB0_457
; #define LAS __attribute__((address_space(3)))
; __device__ __forceinline__ unsigned cvtpk(float lo, float hi) { return pg8::cvt_pk_bf16(lo, hi); }
; __device__ __forceinline__ float bflo(unsigned w) { return __uint_as_float(w << 16); }
; __device__ __forceinline__ float bfhi(unsigned w) { return __uint_as_float(w & 0xffff0000u); }
; __device__ __forceinline__ void transpose_item(const float* __restrict__ W, int K, int N, bf16* __restrict__ WT, LAS float* scr, int item, int lane) {
;     ...
;     const int c = lane & 7;
; #pragma unroll
;     for (int j = 0; j < 4; ++j) { const int n = (lane >> 3) + 8 * j; const LAS float* s = scr + (8 * c) * 33 + n;
;         v4u o; o.x = cvtpk(s[0 * 33], s[1 * 33]); o.y = cvtpk(s[2 * 33], s[3 * 33]); o.z = cvtpk(s[4 * 33], s[5 * 33]); o.w = cvtpk(s[6 * 33], s[7 * 33]);
;         *(v4u*)(WT + (size_t)(n0 + n) * K + k0 + 8 * c) = o; }
; __device__ __forceinline__ void fold_rows(const bf16* __restrict__ Wt, const float* __restrict__ g, const float* __restrict__ b, float* __restrict__ c, float* __restrict__ d, int r0, int r1, int lane) {
;     ...
;         for (int j = 0; j < 4; ++j)
; #pragma unroll
;             for (int e = 0; e < 4; ++e) { const float lo = bflo(w[j][e]), hi = bfhi(w[j][e]); cs += gr[j][2 * e] * lo + gr[j][2 * e + 1] * hi; ds += br[j][2 * e] * lo + br[j][2 * e + 1] * hi; }
	s_mul_hi_i32 s1, s0, 0x1400000
	s_mul_i32 s0, s0, 0x1400000
	v_readlane_b32 s5, v253, 48
	s_waitcnt lgkmcnt(0)
	s_add_u32 s5, s5, s0
	v_readlane_b32 s0, v253, 49
	ds_read2_b32 v[18:19], v5 offset0:33 offset1:41
	ds_read2_b32 v[20:21], v5 offset1:8
	ds_read2_b32 v[22:23], v5 offset0:66 offset1:74
	ds_read2_b32 v[24:25], v5 offset0:99 offset1:107
	ds_read2_b32 v[26:27], v5 offset0:132 offset1:140
	ds_read2_b32 v[28:29], v5 offset0:165 offset1:173
	ds_read2_b32 v[30:31], v5 offset0:198 offset1:206
	ds_read2_b32 v[32:33], v5 offset0:231 offset1:239
	s_addc_u32 s6, s0, s1
	s_lshl_b64 s[0:1], s[34:35], 1
	s_add_u32 s0, s5, s0
	v_or_b32_e32 v34, s30, v3
	s_addc_u32 s1, s6, s1
	v_lshlrev_b32_e32 v10, 1, v6
	v_mov_b32_e32 v11, v85
	v_ashrrev_i32_e32 v35, 31, v34
	v_lshl_add_u64 v[10:11], s[0:1], 0, v[10:11]
	v_lshlrev_b64 v[34:35], 12, v[34:35]
	s_waitcnt lgkmcnt(6)
	v_cvt_pk_bf16_f32 v14, v20, v18
	s_waitcnt lgkmcnt(4)
	v_cvt_pk_bf16_f32 v15, v22, v24
	s_waitcnt lgkmcnt(2)
	v_cvt_pk_bf16_f32 v16, v26, v28
	s_waitcnt lgkmcnt(0)
	v_cvt_pk_bf16_f32 v17, v30, v32
	v_lshl_add_u64 v[34:35], v[10:11], 0, v[34:35]
	v_or_b32_e32 v18, s30, v7
	global_store_dwordx4 v[34:35], v[14:17], off nt
	v_lshlrev_b32_e32 v110, 16, v14
	v_and_b32_e32 v111, 0xffff0000, v14
	v_lshlrev_b32_e32 v112, 16, v15
	v_and_b32_e32 v113, 0xffff0000, v15
	v_lshlrev_b32_e32 v114, 16, v16
	v_and_b32_e32 v115, 0xffff0000, v16
	v_lshlrev_b32_e32 v116, 16, v17
	v_and_b32_e32 v117, 0xffff0000, v17
	v_mul_f32_e32 v118, v94, v110
	v_mul_f32_e32 v119, v102, v110
	v_fmac_f32_e32 v118, v95, v111
	v_fmac_f32_e32 v119, v103, v111
	v_fmac_f32_e32 v118, v96, v112
	v_fmac_f32_e32 v119, v104, v112
	v_fmac_f32_e32 v118, v97, v113
	v_fmac_f32_e32 v119, v105, v113
	v_fmac_f32_e32 v118, v98, v114
	v_fmac_f32_e32 v119, v106, v114
	v_fmac_f32_e32 v118, v99, v115
	v_fmac_f32_e32 v119, v107, v115
	v_fmac_f32_e32 v118, v100, v116
	v_fmac_f32_e32 v119, v108, v116
	v_fmac_f32_e32 v118, v101, v117
	v_fmac_f32_e32 v119, v109, v117
	v_readlane_b32 s50, v254, 61
	v_readlane_b32 s12, v255, 0
	v_cvt_pk_bf16_f32 v14, v21, v19
	v_ashrrev_i32_e32 v19, 31, v18
	v_cvt_pk_bf16_f32 v15, v23, v25
	v_cvt_pk_bf16_f32 v16, v27, v29
	v_cvt_pk_bf16_f32 v17, v31, v33
	v_lshlrev_b64 v[18:19], 12, v[18:19]
	ds_read2_b32 v[20:21], v5 offset0:49 offset1:57
	ds_read2_b32 v[22:23], v5 offset0:16 offset1:24
	ds_read2_b32 v[24:25], v5 offset0:82 offset1:90
	ds_read2_b32 v[26:27], v5 offset0:115 offset1:123
	ds_read2_b32 v[28:29], v5 offset0:148 offset1:156
	ds_read2_b32 v[30:31], v5 offset0:181 offset1:189
	ds_read2_b32 v[32:33], v5 offset0:214 offset1:222
	ds_read2_b32 v[34:35], v5 offset0:247 offset1:255
	v_lshl_add_u64 v[18:19], v[10:11], 0, v[18:19]
	global_store_dwordx4 v[18:19], v[14:17], off nt
	v_lshlrev_b32_e32 v110, 16, v14
	v_and_b32_e32 v111, 0xffff0000, v14
	v_lshlrev_b32_e32 v112, 16, v15
	v_and_b32_e32 v113, 0xffff0000, v15
	v_lshlrev_b32_e32 v114, 16, v16
	v_and_b32_e32 v115, 0xffff0000, v16
	v_lshlrev_b32_e32 v116, 16, v17
	v_and_b32_e32 v117, 0xffff0000, v17
	v_mul_f32_e32 v120, v94, v110
	v_mul_f32_e32 v121, v102, v110
	v_fmac_f32_e32 v120, v95, v111
	v_fmac_f32_e32 v121, v103, v111
	v_fmac_f32_e32 v120, v96, v112
	v_fmac_f32_e32 v121, v104, v112
	v_fmac_f32_e32 v120, v97, v113
	v_fmac_f32_e32 v121, v105, v113
	v_fmac_f32_e32 v120, v98, v114
	v_fmac_f32_e32 v121, v106, v114
	v_fmac_f32_e32 v120, v99, v115
	v_fmac_f32_e32 v121, v107, v115
	v_fmac_f32_e32 v120, v100, v116
	v_fmac_f32_e32 v121, v108, v116
	v_fmac_f32_e32 v120, v101, v117
	v_fmac_f32_e32 v121, v109, v117
	v_or_b32_e32 v18, s30, v12
	v_ashrrev_i32_e32 v19, 31, v18
	v_lshlrev_b64 v[18:19], 12, v[18:19]
	s_waitcnt lgkmcnt(6)
	v_cvt_pk_bf16_f32 v14, v22, v20
	s_waitcnt lgkmcnt(4)
	v_cvt_pk_bf16_f32 v15, v24, v26
	s_waitcnt lgkmcnt(2)
	v_cvt_pk_bf16_f32 v16, v28, v30
	s_waitcnt lgkmcnt(0)
; #define LAS __attribute__((address_space(3)))
; __device__ __forceinline__ unsigned cvtpk(float lo, float hi) { return pg8::cvt_pk_bf16(lo, hi); }
; __device__ __forceinline__ void transpose_item(const float* __restrict__ W, int K, int N, bf16* __restrict__ WT, LAS float* scr, int item, int lane) {
;     ...
;     for (int j = 0; j < 4; ++j) { const int n = (lane >> 3) + 8 * j; const LAS float* s = scr + (8 * c) * 33 + n;
;         v4u o; o.x = cvtpk(s[0 * 33], s[1 * 33]); o.y = cvtpk(s[2 * 33], s[3 * 33]); o.z = cvtpk(s[4 * 33], s[5 * 33]); o.w = cvtpk(s[6 * 33], s[7 * 33]);
;         *(v4u*)(WT + (size_t)(n0 + n) * K + k0 + 8 * c) = o; }
;     asm volatile("s_waitcnt lgkmcnt(0)" ::: "memory");
; __device__ __forceinline__ void fold_rows(const bf16* __restrict__ Wt, const float* __restrict__ g, const float* __restrict__ b, float* __restrict__ c, float* __restrict__ d, int r0, int r1, int lane) {
;     ...
;         cs = wave_sum(cs); ds = wave_sum(ds);
;         if (lane == 0) { c[r] = cs; d[r] = ds; } }
	v_cvt_pk_bf16_f32 v17, v32, v34
	v_lshl_add_u64 v[18:19], v[10:11], 0, v[18:19]
	global_store_dwordx4 v[18:19], v[14:17], off nt
	v_lshlrev_b32_e32 v110, 16, v14
	v_and_b32_e32 v111, 0xffff0000, v14
	v_lshlrev_b32_e32 v112, 16, v15
	v_and_b32_e32 v113, 0xffff0000, v15
	v_lshlrev_b32_e32 v114, 16, v16
	v_and_b32_e32 v115, 0xffff0000, v16
	v_lshlrev_b32_e32 v116, 16, v17
	v_and_b32_e32 v117, 0xffff0000, v17
	v_mul_f32_e32 v122, v94, v110
	v_mul_f32_e32 v123, v102, v110
	v_fmac_f32_e32 v122, v95, v111
	v_fmac_f32_e32 v123, v103, v111
	v_fmac_f32_e32 v122, v96, v112
	v_fmac_f32_e32 v123, v104, v112
	v_fmac_f32_e32 v122, v97, v113
	v_fmac_f32_e32 v123, v105, v113
	v_fmac_f32_e32 v122, v98, v114
	v_fmac_f32_e32 v123, v106, v114
	v_fmac_f32_e32 v122, v99, v115
	v_fmac_f32_e32 v123, v107, v115
	v_fmac_f32_e32 v122, v100, v116
	v_fmac_f32_e32 v123, v108, v116
	v_fmac_f32_e32 v122, v101, v117
	v_fmac_f32_e32 v123, v109, v117
	v_or_b32_e32 v18, s30, v13
	v_ashrrev_i32_e32 v19, 31, v18
	v_lshlrev_b64 v[18:19], 12, v[18:19]
	v_cvt_pk_bf16_f32 v14, v23, v21
	v_cvt_pk_bf16_f32 v15, v25, v27
	v_cvt_pk_bf16_f32 v16, v29, v31
	v_cvt_pk_bf16_f32 v17, v33, v35
	v_lshl_add_u64 v[10:11], v[10:11], 0, v[18:19]
	global_store_dwordx4 v[10:11], v[14:17], off nt
	v_lshlrev_b32_e32 v110, 16, v14
	v_and_b32_e32 v111, 0xffff0000, v14
	v_lshlrev_b32_e32 v112, 16, v15
	v_and_b32_e32 v113, 0xffff0000, v15
	v_lshlrev_b32_e32 v114, 16, v16
	v_and_b32_e32 v115, 0xffff0000, v16
	v_lshlrev_b32_e32 v116, 16, v17
	v_and_b32_e32 v117, 0xffff0000, v17
	v_mul_f32_e32 v124, v94, v110
	v_mul_f32_e32 v125, v102, v110
	v_fmac_f32_e32 v124, v95, v111
	v_fmac_f32_e32 v125, v103, v111
	v_fmac_f32_e32 v124, v96, v112
	v_fmac_f32_e32 v125, v104, v112
	v_fmac_f32_e32 v124, v97, v113
	v_fmac_f32_e32 v125, v105, v113
	v_fmac_f32_e32 v124, v98, v114
	v_fmac_f32_e32 v125, v106, v114
	v_fmac_f32_e32 v124, v99, v115
	v_fmac_f32_e32 v125, v107, v115
	v_fmac_f32_e32 v124, v100, v116
	v_fmac_f32_e32 v125, v108, v116
	v_fmac_f32_e32 v124, v101, v117
	v_fmac_f32_e32 v125, v109, v117
	v_add_f32_dpp v118, v118, v118 quad_perm:[1,0,3,2] row_mask:0xf bank_mask:0xf
	v_add_f32_dpp v119, v119, v119 quad_perm:[1,0,3,2] row_mask:0xf bank_mask:0xf
	v_add_f32_dpp v120, v120, v120 quad_perm:[1,0,3,2] row_mask:0xf bank_mask:0xf
	v_add_f32_dpp v121, v121, v121 quad_perm:[1,0,3,2] row_mask:0xf bank_mask:0xf
	v_add_f32_dpp v122, v122, v122 quad_perm:[1,0,3,2] row_mask:0xf bank_mask:0xf
	v_add_f32_dpp v123, v123, v123 quad_perm:[1,0,3,2] row_mask:0xf bank_mask:0xf
	v_add_f32_dpp v124, v124, v124 quad_perm:[1,0,3,2] row_mask:0xf bank_mask:0xf
	v_add_f32_dpp v125, v125, v125 quad_perm:[1,0,3,2] row_mask:0xf bank_mask:0xf
	v_add_f32_dpp v118, v118, v118 quad_perm:[2,3,0,1] row_mask:0xf bank_mask:0xf
	v_add_f32_dpp v119, v119, v119 quad_perm:[2,3,0,1] row_mask:0xf bank_mask:0xf
	v_add_f32_dpp v120, v120, v120 quad_perm:[2,3,0,1] row_mask:0xf bank_mask:0xf
	v_add_f32_dpp v121, v121, v121 quad_perm:[2,3,0,1] row_mask:0xf bank_mask:0xf
	v_add_f32_dpp v122, v122, v122 quad_perm:[2,3,0,1] row_mask:0xf bank_mask:0xf
	v_add_f32_dpp v123, v123, v123 quad_perm:[2,3,0,1] row_mask:0xf bank_mask:0xf
	v_add_f32_dpp v124, v124, v124 quad_perm:[2,3,0,1] row_mask:0xf bank_mask:0xf
	v_add_f32_dpp v125, v125, v125 quad_perm:[2,3,0,1] row_mask:0xf bank_mask:0xf
	v_add_f32_dpp v118, v118, v118 row_half_mirror row_mask:0xf bank_mask:0xf
	v_add_f32_dpp v119, v119, v119 row_half_mirror row_mask:0xf bank_mask:0xf
	v_add_f32_dpp v120, v120, v120 row_half_mirror row_mask:0xf bank_mask:0xf
	v_add_f32_dpp v121, v121, v121 row_half_mirror row_mask:0xf bank_mask:0xf
	v_add_f32_dpp v122, v122, v122 row_half_mirror row_mask:0xf bank_mask:0xf
	v_add_f32_dpp v123, v123, v123 row_half_mirror row_mask:0xf bank_mask:0xf
	v_add_f32_dpp v124, v124, v124 row_half_mirror row_mask:0xf bank_mask:0xf
	v_add_f32_dpp v125, v125, v125 row_half_mirror row_mask:0xf bank_mask:0xf
	v_cmp_eq_u32_e32 vcc, 0, v6
	s_and_saveexec_b64 s[36:37], vcc
	s_lshl_b32 s100, s101, 5
	s_lshr_b32 s38, s34, 6
	s_add_i32 s100, s100, s38
	s_mul_i32 s100, s100, 0x1400
	s_add_i32 s100, s100, s30
	s_lshl_b32 s100, s100, 3
	s_add_u32 s38, s20, 0x1ac00000
	s_addc_u32 s39, s21, 0
	v_lshlrev_b32_e32 v126, 3, v3
	v_add_u32_e32 v126, s100, v126
	global_store_dwordx2 v126, v[118:119], s[38:39]
	global_store_dwordx2 v126, v[120:121], s[38:39] offset:64
	global_store_dwordx2 v126, v[122:123], s[38:39] offset:128
	global_store_dwordx2 v126, v[124:125], s[38:39] offset:192
	s_or_b64 exec, exec, s[36:37]
	s_waitcnt lgkmcnt(0)
	s_movk_i32 s17, 0x1000
	v_readlane_b32 s51, v254, 62
	v_readlane_b32 s13, v255, 1
	s_branch .LBB0_438
